# memory-attention unit loop: QK key fragments kept 8 reads in flight in a register ring, V fragments double-buffered and prefetched behind the softmax / previous group (was one LDS latency per MFMA)
# speedup vs baseline: 1.0184x; 1.0047x over previous
; #define SBAR() __builtin_amdgcn_sched_barrier(0)
; #define PK4(P, BASE, OUT) do { u32x4 w = {cvtpk(P[BASE + 0], P[BASE + 1]), cvtpk(P[BASE + 2], P[BASE + 3]), cvtpk(P[BASE + 4], P[BASE + 5]), cvtpk(P[BASE + 6], P[BASE + 7])}; \
;     OUT = *reinterpret_cast<bf16x8*>(&w); } while (0)
; __device__ __forceinline__ void exp_half(f32x16& p) {
; #pragma unroll
;     for (int r = 0; r < 16; ++r) p[r] = __builtin_amdgcn_exp2f(p[r]);
; }
; __device__ __forceinline__ void pack_p(const f32x16& p0, const f32x16& p1, float& l_reg, bf16x8& pa0, bf16x8& pa1, bf16x8& pa2, bf16x8& pa3) {
;     float ps = 0;
; #pragma unroll
;     for (int r = 0; r < 16; ++r) ps += p0[r];
; #pragma unroll
;     for (int r = 0; r < 16; ++r) ps += p1[r];
;     l_reg += ps;
;     ...
;     PK4(p0, 0, pa0); PK4(p0, 8, pa1); PK4(p1, 0, pa2); PK4(p1, 8, pa3);
;     ...
; }
; template <int ND0> __device__ __forceinline__ void qkt(f32x16& p0, f32x16& p1, const char* Ks, const bf16x8* qr, int r32, int hi, int colB0) {
; #pragma unroll
;     for (int d0 = 0; d0 < ND0; ++d0) { const int cb = colB0 + (d0 * 16 + hi * 8) * 2;
;         const bf16x8 b0 = *reinterpret_cast<const bf16x8*>(Ks + KSWZ(r32, cb));
;         const bf16x8 b1 = *reinterpret_cast<const bf16x8*>(Ks + KSWZ(32 + r32, cb));
;         p0 = __builtin_amdgcn_mfma_f32_32x32x16_bf16(b0, qr[d0], p0, 0, 0, 0);
;         p1 = __builtin_amdgcn_mfma_f32_32x32x16_bf16(b1, qr[d0], p1, 0, 0, 0); }
; }
; __device__ __forceinline__ void mem_unit(const MemArgs& A, int unit, char* lds, int wv) {
;     ...
;     for (int t = 0; t < 4; ++t) {
;         f32x16 p0, p1; bf16x8 pa0, pa1, pa2, pa3;
; #pragma unroll
;         for (int r = 0; r < 16; ++r) { p0[r] = nM2; p1[r] = nM2; }
;         qkt<8>(p0, p1, K_lds + t * SHM_K, qr, r32, hi, 0);
;         exp_half(p0); exp_half(p1); pack_p(p0, p1, l_reg, pa0, pa1, pa2, pa3); SBAR();
;         pv_d0(o, vb0 + t * SHM_V, pa0, pa1, pa2, pa3);
;     }
.LBB0_200:
	s_add_i32 s100, s2, 0x10000
	v_add_u32_e32 v210, s100, v156
	ds_read_b128 v[178:181], v210
	ds_read_b128 v[182:185], v210 offset:8192
	v_add_u32_e32 v210, s100, v155
	ds_read_b128 v[186:189], v210
	ds_read_b128 v[190:193], v210 offset:8192
	v_add_u32_e32 v210, s100, v154
	ds_read_b128 v[194:197], v210
	ds_read_b128 v[198:201], v210 offset:8192
	v_add_u32_e32 v210, s100, v153
	ds_read_b128 v[202:205], v210
	ds_read_b128 v[206:209], v210 offset:8192
	s_waitcnt lgkmcnt(7)
	v_mfma_f32_32x32x16_bf16 v[96:111], v[178:181], v[112:115], v[64:79]
	v_add_u32_e32 v210, s100, v152
	ds_read_b128 v[178:181], v210
	s_waitcnt lgkmcnt(7)
	v_mfma_f32_32x32x16_bf16 v[80:95], v[182:185], v[112:115], v[64:79]
	ds_read_b128 v[182:185], v210 offset:8192
	s_waitcnt lgkmcnt(7)
	v_mfma_f32_32x32x16_bf16 v[96:111], v[186:189], v[116:119], v[96:111]
	v_add_u32_e32 v210, s100, v151
	ds_read_b128 v[186:189], v210
	s_waitcnt lgkmcnt(7)
	v_mfma_f32_32x32x16_bf16 v[80:95], v[190:193], v[116:119], v[80:95]
	ds_read_b128 v[190:193], v210 offset:8192
	s_waitcnt lgkmcnt(7)
	v_mfma_f32_32x32x16_bf16 v[96:111], v[194:197], v[120:123], v[96:111]
	v_add_u32_e32 v210, s100, v150
	ds_read_b128 v[194:197], v210
	s_waitcnt lgkmcnt(7)
	v_mfma_f32_32x32x16_bf16 v[80:95], v[198:201], v[120:123], v[80:95]
	ds_read_b128 v[198:201], v210 offset:8192
	s_waitcnt lgkmcnt(7)
	v_mfma_f32_32x32x16_bf16 v[96:111], v[202:205], v[124:127], v[96:111]
	v_add_u32_e32 v210, s100, v149
	ds_read_b128 v[202:205], v210
	s_waitcnt lgkmcnt(7)
	v_mfma_f32_32x32x16_bf16 v[80:95], v[206:209], v[124:127], v[80:95]
	ds_read_b128 v[206:209], v210 offset:8192
	s_waitcnt lgkmcnt(7)
	v_mfma_f32_32x32x16_bf16 v[96:111], v[178:181], v[128:131], v[96:111]
	s_waitcnt lgkmcnt(6)
	v_mfma_f32_32x32x16_bf16 v[80:95], v[182:185], v[128:131], v[80:95]
	s_waitcnt lgkmcnt(5)
	v_mfma_f32_32x32x16_bf16 v[96:111], v[186:189], v[132:135], v[96:111]
	s_waitcnt lgkmcnt(4)
	v_mfma_f32_32x32x16_bf16 v[80:95], v[190:193], v[132:135], v[80:95]
	s_waitcnt lgkmcnt(3)
	v_mfma_f32_32x32x16_bf16 v[96:111], v[194:197], v[136:139], v[96:111]
	s_waitcnt lgkmcnt(2)
	v_mfma_f32_32x32x16_bf16 v[80:95], v[198:201], v[136:139], v[80:95]
	s_waitcnt lgkmcnt(1)
	v_mfma_f32_32x32x16_bf16 v[96:111], v[202:205], v[140:143], v[96:111]
	s_waitcnt lgkmcnt(0)
	v_mfma_f32_32x32x16_bf16 v[80:95], v[206:209], v[140:143], v[80:95]
	v_add_u32_e32 v211, s2, v147
	ds_read_b64_tr_b16 v[178:179], v211 offset:0
	ds_read_b64_tr_b16 v[180:181], v211 offset:2048
	ds_read_b64_tr_b16 v[182:183], v211 offset:512
	ds_read_b64_tr_b16 v[184:185], v211 offset:2560
	ds_read_b64_tr_b16 v[186:187], v211 offset:1024
	ds_read_b64_tr_b16 v[188:189], v211 offset:3072
	ds_read_b64_tr_b16 v[190:191], v211 offset:1536
	ds_read_b64_tr_b16 v[192:193], v211 offset:3584
	s_nop 9
	v_exp_f32_e32 v96, v96
	v_exp_f32_e32 v97, v97
	v_exp_f32_e32 v98, v98
	v_exp_f32_e32 v99, v99
	v_exp_f32_e32 v100, v100
	v_exp_f32_e32 v101, v101
	v_exp_f32_e32 v102, v102
	v_exp_f32_e32 v157, v80
	v_add_f32_e32 v80, 0, v96
	v_add_f32_e32 v80, v97, v80
	v_add_f32_e32 v80, v98, v80
	v_exp_f32_e32 v103, v103
	v_add_f32_e32 v80, v99, v80
	v_exp_f32_e32 v104, v104
	v_add_f32_e32 v80, v100, v80
	v_exp_f32_e32 v105, v105
	v_add_f32_e32 v80, v101, v80
	v_exp_f32_e32 v106, v106
	v_add_f32_e32 v80, v102, v80
	v_exp_f32_e32 v107, v107
	v_add_f32_e32 v80, v103, v80
	v_exp_f32_e32 v108, v108
	v_add_f32_e32 v80, v104, v80
	v_exp_f32_e32 v109, v109
	v_add_f32_e32 v80, v105, v80
	v_exp_f32_e32 v110, v110
	v_add_f32_e32 v80, v106, v80
	v_exp_f32_e32 v111, v111
	v_add_f32_e32 v80, v107, v80
	v_add_f32_e32 v80, v108, v80
	v_exp_f32_e32 v158, v81
	v_add_f32_e32 v80, v109, v80
	v_exp_f32_e32 v159, v82
	v_add_f32_e32 v80, v110, v80
	v_exp_f32_e32 v160, v83
	v_add_f32_e32 v80, v111, v80
	v_exp_f32_e32 v161, v84
	v_add_f32_e32 v80, v157, v80
	v_exp_f32_e32 v162, v85
	v_add_f32_e32 v80, v158, v80
	v_exp_f32_e32 v163, v86
	v_add_f32_e32 v80, v159, v80
	v_exp_f32_e32 v164, v87
	v_add_f32_e32 v80, v160, v80
	v_exp_f32_e32 v165, v88
	v_add_f32_e32 v80, v161, v80
	v_exp_f32_e32 v166, v89
	v_add_f32_e32 v80, v162, v80
	v_exp_f32_e32 v167, v90
	v_add_f32_e32 v80, v163, v80
	v_exp_f32_e32 v168, v91
	v_add_f32_e32 v80, v164, v80
	v_exp_f32_e32 v169, v92
	v_add_f32_e32 v80, v165, v80
	v_exp_f32_e32 v170, v93
	v_add_f32_e32 v80, v166, v80
	v_exp_f32_e32 v171, v94
	v_add_f32_e32 v80, v167, v80
	v_exp_f32_e32 v95, v95
	v_add_f32_e32 v80, v168, v80
	v_add_f32_e32 v80, v169, v80
	v_add_f32_e32 v80, v170, v80
	v_add_f32_e32 v80, v171, v80
	v_add_f32_e32 v80, v95, v80
	v_add_f32_e32 v148, v148, v80
	v_cvt_pk_bf16_f32 v80, v96, v97
	v_cvt_pk_bf16_f32 v81, v98, v99
	v_cvt_pk_bf16_f32 v82, v100, v101
	v_cvt_pk_bf16_f32 v83, v102, v103
	v_cvt_pk_bf16_f32 v84, v104, v105
	v_cvt_pk_bf16_f32 v85, v106, v107
	v_cvt_pk_bf16_f32 v86, v108, v109
	v_cvt_pk_bf16_f32 v87, v110, v111
	v_cvt_pk_bf16_f32 v88, v157, v158
	v_cvt_pk_bf16_f32 v89, v159, v160
	v_cvt_pk_bf16_f32 v90, v161, v162
	v_cvt_pk_bf16_f32 v91, v163, v164
	v_cvt_pk_bf16_f32 v92, v165, v166
	v_cvt_pk_bf16_f32 v93, v167, v168
	v_cvt_pk_bf16_f32 v94, v169, v170
	v_cvt_pk_bf16_f32 v95, v171, v95
	s_setprio 1
	s_waitcnt lgkmcnt(6)
	v_mfma_f32_32x32x16_bf16 v[48:63], v[80:83], v[178:181], v[48:63]
	ds_read_b64_tr_b16 v[194:195], v211 offset:4096
	ds_read_b64_tr_b16 v[196:197], v211 offset:6144
	s_waitcnt lgkmcnt(6)
	v_mfma_f32_32x32x16_bf16 v[32:47], v[80:83], v[182:185], v[32:47]
	ds_read_b64_tr_b16 v[198:199], v211 offset:4608
	ds_read_b64_tr_b16 v[200:201], v211 offset:6656
	s_waitcnt lgkmcnt(6)
	v_mfma_f32_32x32x16_bf16 v[16:31], v[80:83], v[186:189], v[16:31]
	ds_read_b64_tr_b16 v[202:203], v211 offset:5120
	ds_read_b64_tr_b16 v[204:205], v211 offset:7168
	s_waitcnt lgkmcnt(6)
; #define SBAR() __builtin_amdgcn_sched_barrier(0)
; __device__ __forceinline__ int crow(int r, int hi) { return (r & 3) + 8 * (r >> 2) + 4 * hi; }
; __device__ __forceinline__ float bf2f(unsigned short h) { return __uint_as_float(((unsigned)h) << 16); }
; template <int KS> __device__ __forceinline__ void pv_ks(f32x16* o, int vb, bf16x8 pa) {
;     const s16x4 l0 = tr_read<v_rd_off(0, KS, 0)>(vb), h0 = tr_read<v_rd_off(0, KS, 1)>(vb), l1 = tr_read<v_rd_off(1, KS, 0)>(vb), h1 = tr_read<v_rd_off(1, KS, 1)>(vb);
;     const s16x4 l2 = tr_read<v_rd_off(2, KS, 0)>(vb), h2 = tr_read<v_rd_off(2, KS, 1)>(vb), l3 = tr_read<v_rd_off(3, KS, 0)>(vb), h3 = tr_read<v_rd_off(3, KS, 1)>(vb);
;     ...
;     asm volatile("s_waitcnt lgkmcnt(6)" ::: "memory"); SBAR();
;     o[0] = __builtin_amdgcn_mfma_f32_32x32x16_bf16(pa, PK(l0, h0), o[0], 0, 0, 0);
;     asm volatile("s_waitcnt lgkmcnt(4)" ::: "memory"); SBAR();
;     o[1] = __builtin_amdgcn_mfma_f32_32x32x16_bf16(pa, PK(l1, h1), o[1], 0, 0, 0);
;     asm volatile("s_waitcnt lgkmcnt(2)" ::: "memory"); SBAR();
;     o[2] = __builtin_amdgcn_mfma_f32_32x32x16_bf16(pa, PK(l2, h2), o[2], 0, 0, 0);
;     asm volatile("s_waitcnt lgkmcnt(0)" ::: "memory"); SBAR();
;     o[3] = __builtin_amdgcn_mfma_f32_32x32x16_bf16(pa, PK(l3, h3), o[3], 0, 0, 0);
;     ...
; }
; __device__ __forceinline__ void pv_d0(f32x16* o, int vb, bf16x8 pa0, bf16x8 pa1, bf16x8 pa2, bf16x8 pa3) {
;     __builtin_amdgcn_s_setprio(1);
;     pv_ks<0>(o, vb, pa0); pv_ks<1>(o, vb, pa1); pv_ks<2>(o, vb, pa2); pv_ks<3>(o, vb, pa3);
;     __builtin_amdgcn_s_setprio(0);
; }
; __device__ __forceinline__ void mem_unit(const MemArgs& A, int unit, char* lds, int wv) {
;     ...
;     { auto rr = __builtin_amdgcn_permlane32_swap(__float_as_uint(l_reg), __float_as_uint(l_reg), false, false);
;       l_reg = __uint_as_float(rr[0]) + __uint_as_float(rr[1]); }
;     if (hi == 0) wsl[r32] = l_reg;
;     asm volatile("s_waitcnt lgkmcnt(0)" ::: "memory");
; #pragma unroll
;     for (int r = 0; r < 16; ++r) { const int rr_ = crow(r, hi); const float rl = 1.0f / wsl[rr_];
;         const bf16* gp = A.proj + (grow0 + rr_) * INC + C_MG + hm * 128 + r32; bf16* yp = A.y + (grow0 + rr_) * DM + Y_M + hm * 128 + r32;
; #pragma unroll
;         for (int d0 = 0; d0 < 4; ++d0) { const float g = bf2f(gp[d0 * 32]); const float val = o[d0][r] * rl * silu(g);
;             yp[d0 * 32] = (bf16)(cvtpk(val, val) & 0xffffu); } }
	v_mfma_f32_32x32x16_bf16 v[0:15], v[80:83], v[190:193], v[0:15]
	ds_read_b64_tr_b16 v[206:207], v211 offset:5632
	ds_read_b64_tr_b16 v[208:209], v211 offset:7680
	s_waitcnt lgkmcnt(6)
	v_mfma_f32_32x32x16_bf16 v[48:63], v[84:87], v[194:197], v[48:63]
	ds_read_b64_tr_b16 v[178:179], v211 offset:8192
	ds_read_b64_tr_b16 v[180:181], v211 offset:10240
	s_waitcnt lgkmcnt(6)
	v_mfma_f32_32x32x16_bf16 v[32:47], v[84:87], v[198:201], v[32:47]
	ds_read_b64_tr_b16 v[182:183], v211 offset:8704
	ds_read_b64_tr_b16 v[184:185], v211 offset:10752
	s_waitcnt lgkmcnt(6)
	v_mfma_f32_32x32x16_bf16 v[16:31], v[84:87], v[202:205], v[16:31]
	ds_read_b64_tr_b16 v[186:187], v211 offset:9216
	ds_read_b64_tr_b16 v[188:189], v211 offset:11264
	s_waitcnt lgkmcnt(6)
	v_mfma_f32_32x32x16_bf16 v[0:15], v[84:87], v[206:209], v[0:15]
	ds_read_b64_tr_b16 v[190:191], v211 offset:9728
	ds_read_b64_tr_b16 v[192:193], v211 offset:11776
	s_waitcnt lgkmcnt(6)
	v_mfma_f32_32x32x16_bf16 v[48:63], v[88:91], v[178:181], v[48:63]
	ds_read_b64_tr_b16 v[194:195], v211 offset:12288
	ds_read_b64_tr_b16 v[196:197], v211 offset:14336
	s_waitcnt lgkmcnt(6)
	v_mfma_f32_32x32x16_bf16 v[32:47], v[88:91], v[182:185], v[32:47]
	ds_read_b64_tr_b16 v[198:199], v211 offset:12800
	ds_read_b64_tr_b16 v[200:201], v211 offset:14848
	s_waitcnt lgkmcnt(6)
	v_mfma_f32_32x32x16_bf16 v[16:31], v[88:91], v[186:189], v[16:31]
	ds_read_b64_tr_b16 v[202:203], v211 offset:13312
	ds_read_b64_tr_b16 v[204:205], v211 offset:15360
	s_waitcnt lgkmcnt(6)
	v_mfma_f32_32x32x16_bf16 v[0:15], v[88:91], v[190:193], v[0:15]
	ds_read_b64_tr_b16 v[206:207], v211 offset:13824
	ds_read_b64_tr_b16 v[208:209], v211 offset:15872
	s_waitcnt lgkmcnt(6)
	v_mfma_f32_32x32x16_bf16 v[48:63], v[92:95], v[194:197], v[48:63]
	s_waitcnt lgkmcnt(4)
	v_mfma_f32_32x32x16_bf16 v[32:47], v[92:95], v[198:201], v[32:47]
	s_waitcnt lgkmcnt(2)
	v_mfma_f32_32x32x16_bf16 v[16:31], v[92:95], v[202:205], v[16:31]
	s_waitcnt lgkmcnt(0)
	v_mfma_f32_32x32x16_bf16 v[0:15], v[92:95], v[206:209], v[0:15]
	s_setprio 0
	s_addk_i32 s2, 0x4000
	s_cmp_lg_u32 s2, 0x10000
	s_cbranch_scc1 .LBB0_200
	s_and_b32 s1, s1, 0x3fffffc0
	s_lshl_b32 s1, s1, 2
	s_add_i32 s1, s1, 0
	v_mov_b32_e32 v64, v148
	s_add_i32 s1, s1, 0x20000
	s_nop 0
	v_permlane32_swap_b32_e32 v148, v64
	v_cmp_gt_u32_e32 vcc, 32, v145
	s_and_saveexec_b64 s[6:7], vcc
	v_add_f32_e32 v64, v148, v64
	v_lshl_add_u32 v65, v144, 2, s1
	ds_write_b32 v65, v64
	s_or_b64 exec, exec, s[6:7]
	s_waitcnt lgkmcnt(0)
	v_lshl_add_u32 v72, v146, 4, s1
	ds_read_b128 v[64:67], v72
	s_lshl_b32 s84, s0, 1
	v_lshlrev_b32_e32 v176, 1, v144
	s_waitcnt lgkmcnt(0)
	v_div_scale_f32 v68, s[6:7], v64, v64, 1.0
	v_rcp_f32_e32 v69, v68
	s_nop 0
	v_fma_f32 v70, -v68, v69, 1.0
	v_fmac_f32_e32 v69, v70, v69
	v_div_scale_f32 v70, vcc, 1.0, v64, 1.0
	v_mul_f32_e32 v71, v70, v69
	v_fma_f32 v73, -v68, v71, v70
	v_fmac_f32_e32 v71, v73, v69
	v_fma_f32 v68, -v68, v71, v70
	v_div_fmas_f32 v68, v68, v69, v71
	v_div_fixup_f32 v64, v68, v64, 1.0
	v_lshl_or_b32 v68, v146, 2, s8
	v_mul_u32_u24_e32 v161, 0x3800, v68
	v_add_u32_e32 v161, s84, v161
	v_lshl_add_u32 v161, v144, 1, v161
	v_add_u32_e32 v161, 0x3400, v161
	global_load_ushort v84, v161, s[80:81]
	global_load_ushort v85, v161, s[80:81] offset:64
	global_load_ushort v86, v161, s[80:81] offset:128
	global_load_ushort v87, v161, s[80:81] offset:192
	v_add_u32_e32 v163, 0x3800, v161
	global_load_ushort v88, v163, s[80:81]
	global_load_ushort v89, v163, s[80:81] offset:64
	global_load_ushort v90, v163, s[80:81] offset:128
	global_load_ushort v91, v163, s[80:81] offset:192
	v_add_u32_e32 v162, 0x7000, v161
	global_load_ushort v92, v162, s[80:81]
	global_load_ushort v93, v162, s[80:81] offset:64
	global_load_ushort v94, v162, s[80:81] offset:128
	global_load_ushort v95, v162, s[80:81] offset:192
	v_add_u32_e32 v163, 0xa800, v161
	global_load_ushort v96, v163, s[80:81]
	global_load_ushort v97, v163, s[80:81] offset:64
	global_load_ushort v98, v163, s[80:81] offset:128
	global_load_ushort v99, v163, s[80:81] offset:192
	v_add_u32_e32 v162, 0x1c000, v161
	global_load_ushort v100, v162, s[80:81]
	global_load_ushort v101, v162, s[80:81] offset:64
	global_load_ushort v102, v162, s[80:81] offset:128
	global_load_ushort v103, v162, s[80:81] offset:192
	v_add_u32_e32 v163, 0x1f800, v161
	global_load_ushort v104, v163, s[80:81]
	global_load_ushort v105, v163, s[80:81] offset:64
	global_load_ushort v106, v163, s[80:81] offset:128
	global_load_ushort v107, v163, s[80:81] offset:192
	v_add_u32_e32 v162, 0x23000, v161
	global_load_ushort v108, v162, s[80:81]
	global_load_ushort v109, v162, s[80:81] offset:64
	global_load_ushort v110, v162, s[80:81] offset:128
	global_load_ushort v111, v162, s[80:81] offset:192
	v_add_u32_e32 v163, 0x26800, v161
	global_load_ushort v157, v163, s[80:81]
	global_load_ushort v158, v163, s[80:81] offset:64
	global_load_ushort v159, v163, s[80:81] offset:128
	global_load_ushort v160, v163, s[80:81] offset:192
	v_mov_b64_e32 v[70:71], s[80:81]
	v_mad_u64_u32 v[74:75], s[6:7], v68, s33, v[70:71]
	s_mul_i32 s6, s3, 0x3800
	s_nop 0
	v_add_u32_e32 v75, s6, v75
	v_lshl_add_u64 v[74:75], v[74:75], 0, s[84:85]
	v_mov_b32_e32 v69, s3
	v_lshl_add_u64 v[74:75], v[74:75], 0, v[176:177]
	s_mov_b64 s[2:3], 0x3400
	v_lshl_add_u64 v[76:77], v[74:75], 0, s[2:3]
	v_add_co_u32_e32 v74, vcc, s63, v74
	v_lshlrev_b64 v[78:79], 12, v[68:69]
	s_nop 0
	v_addc_co_u32_e32 v75, vcc, 0, v75, vcc
	s_waitcnt vmcnt(28)
; __device__ __forceinline__ int crow(int r, int hi) { return (r & 3) + 8 * (r >> 2) + 4 * hi; }
; __device__ __forceinline__ unsigned cvtpk(float lo, float hi) { f32x2_t v = {lo, hi}; bf16x2_t b = __builtin_convertvector(v, bf16x2_t); return __builtin_bit_cast(unsigned, b); }
; __device__ __forceinline__ float bf2f(unsigned short h) { return __uint_as_float(((unsigned)h) << 16); }
; __device__ __forceinline__ float silu(float x) { return x / (1.0f + __expf(-x)); }
; __device__ __forceinline__ void mem_unit(const MemArgs& A, int unit, char* lds, int wv) {
;     ...
;     if (hi == 0) wsl[r32] = l_reg;
;     asm volatile("s_waitcnt lgkmcnt(0)" ::: "memory");
; #pragma unroll
;     for (int r = 0; r < 16; ++r) { const int rr_ = crow(r, hi); const float rl = 1.0f / wsl[rr_];
;         const bf16* gp = A.proj + (grow0 + rr_) * INC + C_MG + hm * 128 + r32; bf16* yp = A.y + (grow0 + rr_) * DM + Y_M + hm * 128 + r32;
; #pragma unroll
;         for (int d0 = 0; d0 < 4; ++d0) { const float g = bf2f(gp[d0 * 32]); const float val = o[d0][r] * rl * silu(g);
;             yp[d0 * 32] = (bf16)(cvtpk(val, val) & 0xffffu); } }
;     __syncthreads();
	v_mov_b32_e32 v73, v84
	v_lshl_add_u64 v[78:79], s[82:83], 0, v[78:79]
	v_mul_f32_e32 v48, v48, v64
	v_lshl_add_u64 v[78:79], v[78:79], 0, s[84:85]
	v_lshl_add_u64 v[78:79], v[78:79], 0, v[176:177]
	v_mul_f32_e32 v32, v32, v64
	v_mul_f32_e32 v16, v16, v64
	v_mul_f32_e32 v0, v0, v64
	s_nop 0
	v_lshlrev_b32_e32 v73, 16, v73
	v_mul_f32_e32 v74, 0xbfb8aa3b, v73
	v_exp_f32_e32 v74, v74
	s_nop 0
	v_add_f32_e32 v74, 1.0, v74
	v_div_scale_f32 v75, s[0:1], v74, v74, v73
	v_rcp_f32_e32 v80, v75
	s_nop 0
	v_fma_f32 v81, -v75, v80, 1.0
	v_fmac_f32_e32 v80, v81, v80
	v_div_scale_f32 v81, vcc, v73, v74, v73
	v_mul_f32_e32 v82, v81, v80
	v_fma_f32 v83, -v75, v82, v81
	v_fmac_f32_e32 v82, v83, v80
	v_fma_f32 v75, -v75, v82, v81
	v_div_fmas_f32 v75, v75, v80, v82
	v_div_fixup_f32 v73, v75, v74, v73
	v_mul_f32_e32 v48, v48, v73
	v_cvt_pk_bf16_f32 v48, v48, s0
	global_store_short v[78:79], v48, off offset:3072
	s_waitcnt vmcnt(28)
	v_mov_b32_e32 v48, v85
	s_nop 0
	v_lshlrev_b32_e32 v48, 16, v48
	v_mul_f32_e32 v73, 0xbfb8aa3b, v48
	v_exp_f32_e32 v73, v73
	s_nop 0
	v_add_f32_e32 v73, 1.0, v73
	v_div_scale_f32 v74, s[0:1], v73, v73, v48
	v_rcp_f32_e32 v75, v74
	s_nop 0
	v_fma_f32 v80, -v74, v75, 1.0
	v_fmac_f32_e32 v75, v80, v75
	v_div_scale_f32 v80, vcc, v48, v73, v48
	v_mul_f32_e32 v81, v80, v75
	v_fma_f32 v82, -v74, v81, v80
	v_fmac_f32_e32 v81, v82, v75
	v_fma_f32 v74, -v74, v81, v80
	v_div_fmas_f32 v74, v74, v75, v81
	v_div_fixup_f32 v48, v74, v73, v48
	v_mul_f32_e32 v32, v32, v48
	v_cvt_pk_bf16_f32 v32, v32, s0
	global_store_short v[78:79], v32, off offset:3136
	s_waitcnt vmcnt(28)
	v_mov_b32_e32 v32, v86
	s_nop 0
	v_lshlrev_b32_e32 v32, 16, v32
	v_mul_f32_e32 v48, 0xbfb8aa3b, v32
	v_exp_f32_e32 v48, v48
	s_nop 0
	v_add_f32_e32 v48, 1.0, v48
	v_div_scale_f32 v73, s[0:1], v48, v48, v32
	v_rcp_f32_e32 v74, v73
	s_nop 0
	v_fma_f32 v75, -v73, v74, 1.0
	v_fmac_f32_e32 v74, v75, v74
	v_div_scale_f32 v75, vcc, v32, v48, v32
	v_mul_f32_e32 v80, v75, v74
	v_fma_f32 v81, -v73, v80, v75
	v_fmac_f32_e32 v80, v81, v74
	v_fma_f32 v73, -v73, v80, v75
	v_div_fmas_f32 v73, v73, v74, v80
	v_div_fixup_f32 v32, v73, v48, v32
	v_mul_f32_e32 v16, v16, v32
	v_cvt_pk_bf16_f32 v16, v16, s0
	global_store_short v[78:79], v16, off offset:3200
	s_waitcnt vmcnt(28)
	v_mov_b32_e32 v16, v87
	s_nop 0
	v_lshlrev_b32_e32 v16, 16, v16
	v_mul_f32_e32 v32, 0xbfb8aa3b, v16
	v_exp_f32_e32 v32, v32
	s_nop 0
	v_add_f32_e32 v32, 1.0, v32
	v_div_scale_f32 v48, s[0:1], v32, v32, v16
	v_rcp_f32_e32 v64, v48
	s_nop 0
	v_fma_f32 v73, -v48, v64, 1.0
	v_fmac_f32_e32 v64, v73, v64
	v_div_scale_f32 v73, vcc, v16, v32, v16
	v_mul_f32_e32 v74, v73, v64
	v_fma_f32 v75, -v48, v74, v73
	v_fmac_f32_e32 v74, v75, v64
	v_fma_f32 v48, -v48, v74, v73
	v_div_fmas_f32 v48, v48, v64, v74
	v_div_fixup_f32 v16, v48, v32, v16
	v_mul_f32_e32 v0, v0, v16
	v_cvt_pk_bf16_f32 v0, v0, s0
	global_store_short v[78:79], v0, off offset:3264
	v_div_scale_f32 v0, s[0:1], v65, v65, 1.0
	v_rcp_f32_e32 v16, v0
	s_nop 0
	v_fma_f32 v32, -v0, v16, 1.0
	v_fmac_f32_e32 v16, v32, v16
	v_div_scale_f32 v32, vcc, 1.0, v65, 1.0
	v_mul_f32_e32 v48, v32, v16
	v_fma_f32 v64, -v0, v48, v32
	v_fmac_f32_e32 v48, v64, v16
	v_or_b32_e32 v64, 1, v68
	v_mad_u64_u32 v[74:75], s[0:1], v64, s33, v[70:71]
	v_add_u32_e32 v75, s6, v75
	v_lshl_add_u64 v[74:75], v[74:75], 0, s[84:85]
	v_fma_f32 v0, -v0, v48, v32
	v_lshl_add_u64 v[74:75], v[74:75], 0, v[176:177]
	v_div_fmas_f32 v0, v0, v16, v48
	v_lshl_add_u64 v[76:77], v[74:75], 0, s[2:3]
	v_add_co_u32_e32 v74, vcc, s63, v74
	v_div_fixup_f32 v0, v0, v65, 1.0
	s_nop 0
	v_addc_co_u32_e32 v75, vcc, 0, v75, vcc
	s_waitcnt vmcnt(28)
	v_mov_b32_e32 v16, v88
	v_mul_f32_e32 v32, v49, v0
	v_mov_b32_e32 v65, v69
	v_lshlrev_b64 v[64:65], 12, v[64:65]
	v_lshl_add_u64 v[64:65], s[82:83], 0, v[64:65]
	v_lshl_add_u64 v[64:65], v[64:65], 0, s[84:85]
	v_lshl_add_u64 v[64:65], v[64:65], 0, v[176:177]
	v_mul_f32_e32 v17, v17, v0
	s_nop 0
	v_lshlrev_b32_e32 v16, 16, v16
	v_mul_f32_e32 v48, 0xbfb8aa3b, v16
	v_exp_f32_e32 v48, v48
	s_nop 0
	v_add_f32_e32 v48, 1.0, v48
	v_div_scale_f32 v49, s[0:1], v48, v48, v16
	v_rcp_f32_e32 v73, v49
	s_nop 0
	v_fma_f32 v74, -v49, v73, 1.0
	v_fmac_f32_e32 v73, v74, v73
	v_div_scale_f32 v74, vcc, v16, v48, v16
	v_mul_f32_e32 v75, v74, v73
	v_fma_f32 v78, -v49, v75, v74
	v_fmac_f32_e32 v75, v78, v73
	v_fma_f32 v49, -v49, v75, v74
	v_div_fmas_f32 v49, v49, v73, v75
	v_div_fixup_f32 v16, v49, v48, v16
	v_mul_f32_e32 v16, v32, v16
	v_cvt_pk_bf16_f32 v16, v16, s0
	global_store_short v[64:65], v16, off offset:3072
	s_waitcnt vmcnt(28)
	v_mov_b32_e32 v16, v89
	v_mul_f32_e32 v32, v33, v0
	v_mul_f32_e32 v0, v1, v0
	s_nop 0
	v_lshlrev_b32_e32 v16, 16, v16
	v_mul_f32_e32 v33, 0xbfb8aa3b, v16
	v_exp_f32_e32 v33, v33
	s_nop 0
	v_add_f32_e32 v33, 1.0, v33
	v_div_scale_f32 v48, s[0:1], v33, v33, v16
	v_rcp_f32_e32 v49, v48
	s_nop 0
	v_fma_f32 v73, -v48, v49, 1.0
	v_fmac_f32_e32 v49, v73, v49
	v_div_scale_f32 v73, vcc, v16, v33, v16
	v_mul_f32_e32 v74, v73, v49
	v_fma_f32 v75, -v48, v74, v73
	v_fmac_f32_e32 v74, v75, v49
	v_fma_f32 v48, -v48, v74, v73
	v_div_fmas_f32 v48, v48, v49, v74
	v_div_fixup_f32 v16, v48, v33, v16
	v_mul_f32_e32 v16, v32, v16
	v_cvt_pk_bf16_f32 v16, v16, s0
	global_store_short v[64:65], v16, off offset:3136
	s_waitcnt vmcnt(28)
	v_mov_b32_e32 v16, v90
	s_nop 0
	v_lshlrev_b32_e32 v16, 16, v16
	v_mul_f32_e32 v32, 0xbfb8aa3b, v16
	v_exp_f32_e32 v32, v32
	s_nop 0
	v_add_f32_e32 v32, 1.0, v32
	v_div_scale_f32 v33, s[0:1], v32, v32, v16
	v_rcp_f32_e32 v48, v33
	s_nop 0
	v_fma_f32 v49, -v33, v48, 1.0
	v_fmac_f32_e32 v48, v49, v48
	v_div_scale_f32 v49, vcc, v16, v32, v16
	v_mul_f32_e32 v73, v49, v48
	v_fma_f32 v74, -v33, v73, v49
	v_fmac_f32_e32 v73, v74, v48
	v_fma_f32 v33, -v33, v73, v49
	v_div_fmas_f32 v33, v33, v48, v73
	v_div_fixup_f32 v16, v33, v32, v16
	v_mul_f32_e32 v16, v17, v16
	v_cvt_pk_bf16_f32 v16, v16, s0
	global_store_short v[64:65], v16, off offset:3200
	s_waitcnt vmcnt(28)
; __device__ __forceinline__ int crow(int r, int hi) { return (r & 3) + 8 * (r >> 2) + 4 * hi; }
; __device__ __forceinline__ unsigned cvtpk(float lo, float hi) { f32x2_t v = {lo, hi}; bf16x2_t b = __builtin_convertvector(v, bf16x2_t); return __builtin_bit_cast(unsigned, b); }
; __device__ __forceinline__ float bf2f(unsigned short h) { return __uint_as_float(((unsigned)h) << 16); }
; __device__ __forceinline__ float silu(float x) { return x / (1.0f + __expf(-x)); }
; __device__ __forceinline__ void mem_unit(const MemArgs& A, int unit, char* lds, int wv) {
;     ...
;     if (hi == 0) wsl[r32] = l_reg;
;     asm volatile("s_waitcnt lgkmcnt(0)" ::: "memory");
; #pragma unroll
;     for (int r = 0; r < 16; ++r) { const int rr_ = crow(r, hi); const float rl = 1.0f / wsl[rr_];
;         const bf16* gp = A.proj + (grow0 + rr_) * INC + C_MG + hm * 128 + r32; bf16* yp = A.y + (grow0 + rr_) * DM + Y_M + hm * 128 + r32;
; #pragma unroll
;         for (int d0 = 0; d0 < 4; ++d0) { const float g = bf2f(gp[d0 * 32]); const float val = o[d0][r] * rl * silu(g);
;             yp[d0 * 32] = (bf16)(cvtpk(val, val) & 0xffffu); } }
;     __syncthreads();
	v_mov_b32_e32 v16, v91
	s_nop 0
	v_lshlrev_b32_e32 v16, 16, v16
	v_mul_f32_e32 v1, 0xbfb8aa3b, v16
	v_exp_f32_e32 v1, v1
	s_nop 0
	v_add_f32_e32 v1, 1.0, v1
	v_div_scale_f32 v17, s[0:1], v1, v1, v16
	v_rcp_f32_e32 v32, v17
	s_nop 0
	v_fma_f32 v33, -v17, v32, 1.0
	v_fmac_f32_e32 v32, v33, v32
	v_div_scale_f32 v33, vcc, v16, v1, v16
	v_mul_f32_e32 v48, v33, v32
	v_fma_f32 v49, -v17, v48, v33
	v_fmac_f32_e32 v48, v49, v32
	v_fma_f32 v17, -v17, v48, v33
	v_div_fmas_f32 v17, v17, v32, v48
	v_div_fixup_f32 v1, v17, v1, v16
	v_mul_f32_e32 v0, v0, v1
	v_cvt_pk_bf16_f32 v0, v0, s0
	global_store_short v[64:65], v0, off offset:3264
	v_div_scale_f32 v0, s[0:1], v66, v66, 1.0
	v_rcp_f32_e32 v1, v0
	s_nop 0
	v_fma_f32 v16, -v0, v1, 1.0
	v_fmac_f32_e32 v1, v16, v1
	v_div_scale_f32 v16, vcc, 1.0, v66, 1.0
	v_mul_f32_e32 v17, v16, v1
	v_fma_f32 v32, -v0, v17, v16
	v_fmac_f32_e32 v17, v32, v1
	v_fma_f32 v0, -v0, v17, v16
	v_div_fmas_f32 v0, v0, v1, v17
	v_div_fixup_f32 v48, v0, v66, 1.0
	v_or_b32_e32 v0, 2, v68
	v_mad_u64_u32 v[16:17], s[0:1], v0, s33, v[70:71]
	v_add_u32_e32 v17, s6, v17
	v_lshl_add_u64 v[16:17], v[16:17], 0, s[84:85]
	v_lshl_add_u64 v[16:17], v[16:17], 0, v[176:177]
	v_lshl_add_u64 v[32:33], v[16:17], 0, s[2:3]
	v_add_co_u32_e32 v16, vcc, s63, v16
	v_mov_b32_e32 v1, v69
	s_nop 0
	v_addc_co_u32_e32 v17, vcc, 0, v17, vcc
	s_waitcnt vmcnt(28)
	v_mov_b32_e32 v16, v92
	v_mul_f32_e32 v17, v50, v48
	v_lshlrev_b64 v[0:1], 12, v[0:1]
	v_lshl_add_u64 v[0:1], s[82:83], 0, v[0:1]
	v_lshl_add_u64 v[0:1], v[0:1], 0, s[84:85]
	v_lshl_add_u64 v[0:1], v[0:1], 0, v[176:177]
	v_mul_f32_e32 v2, v2, v48
	s_nop 0
	v_lshlrev_b32_e32 v16, 16, v16
	v_mul_f32_e32 v49, 0xbfb8aa3b, v16
	v_exp_f32_e32 v49, v49
	s_nop 0
	v_add_f32_e32 v49, 1.0, v49
	v_div_scale_f32 v50, s[0:1], v49, v49, v16
	v_rcp_f32_e32 v64, v50
	s_nop 0
	v_fma_f32 v65, -v50, v64, 1.0
	v_fmac_f32_e32 v64, v65, v64
	v_div_scale_f32 v65, vcc, v16, v49, v16
	v_mul_f32_e32 v66, v65, v64
	v_fma_f32 v73, -v50, v66, v65
	v_fmac_f32_e32 v66, v73, v64
	v_fma_f32 v50, -v50, v66, v65
	v_div_fmas_f32 v50, v50, v64, v66
	v_div_fixup_f32 v16, v50, v49, v16
	v_mul_f32_e32 v16, v17, v16
	v_cvt_pk_bf16_f32 v16, v16, s0
	global_store_short v[0:1], v16, off offset:3072
	s_waitcnt vmcnt(28)
	v_mov_b32_e32 v16, v93
	v_mul_f32_e32 v17, v34, v48
	s_nop 0
	v_lshlrev_b32_e32 v16, 16, v16
	v_mul_f32_e32 v34, 0xbfb8aa3b, v16
	v_exp_f32_e32 v34, v34
	s_nop 0
	v_add_f32_e32 v34, 1.0, v34
	v_div_scale_f32 v49, s[0:1], v34, v34, v16
	v_rcp_f32_e32 v50, v49
	s_nop 0
	v_fma_f32 v64, -v49, v50, 1.0
	v_fmac_f32_e32 v50, v64, v50
	v_div_scale_f32 v64, vcc, v16, v34, v16
	v_mul_f32_e32 v65, v64, v50
	v_fma_f32 v66, -v49, v65, v64
	v_fmac_f32_e32 v65, v66, v50
	v_fma_f32 v49, -v49, v65, v64
	v_div_fmas_f32 v49, v49, v50, v65
	v_div_fixup_f32 v16, v49, v34, v16
	v_mul_f32_e32 v16, v17, v16
	v_cvt_pk_bf16_f32 v16, v16, s0
	global_store_short v[0:1], v16, off offset:3136
	s_waitcnt vmcnt(28)
	v_mov_b32_e32 v16, v94
	v_mul_f32_e32 v17, v18, v48
	s_nop 0
	v_lshlrev_b32_e32 v16, 16, v16
	v_mul_f32_e32 v18, 0xbfb8aa3b, v16
	v_exp_f32_e32 v18, v18
	s_nop 0
	v_add_f32_e32 v18, 1.0, v18
	v_div_scale_f32 v34, s[0:1], v18, v18, v16
	v_rcp_f32_e32 v49, v34
	s_nop 0
	v_fma_f32 v50, -v34, v49, 1.0
	v_fmac_f32_e32 v49, v50, v49
	v_div_scale_f32 v50, vcc, v16, v18, v16
	v_mul_f32_e32 v64, v50, v49
	v_fma_f32 v65, -v34, v64, v50
	v_fmac_f32_e32 v64, v65, v49
	v_fma_f32 v34, -v34, v64, v50
	v_div_fmas_f32 v34, v34, v49, v64
	v_div_fixup_f32 v16, v34, v18, v16
	v_mul_f32_e32 v16, v17, v16
	v_cvt_pk_bf16_f32 v16, v16, s0
	global_store_short v[0:1], v16, off offset:3200
	s_waitcnt vmcnt(28)
	v_mov_b32_e32 v16, v95
	s_nop 0
	v_lshlrev_b32_e32 v16, 16, v16
	v_mul_f32_e32 v17, 0xbfb8aa3b, v16
	v_exp_f32_e32 v17, v17
	s_nop 0
	v_add_f32_e32 v17, 1.0, v17
	v_div_scale_f32 v18, s[0:1], v17, v17, v16
	v_rcp_f32_e32 v32, v18
	s_nop 0
	v_fma_f32 v33, -v18, v32, 1.0
	v_fmac_f32_e32 v32, v33, v32
	v_div_scale_f32 v33, vcc, v16, v17, v16
	v_mul_f32_e32 v34, v33, v32
	v_fma_f32 v48, -v18, v34, v33
	v_fmac_f32_e32 v34, v48, v32
	v_fma_f32 v18, -v18, v34, v33
	v_div_fmas_f32 v18, v18, v32, v34
	v_div_fixup_f32 v16, v18, v17, v16
	v_mul_f32_e32 v2, v2, v16
	v_cvt_pk_bf16_f32 v2, v2, s0
	global_store_short v[0:1], v2, off offset:3264
	v_div_scale_f32 v0, s[0:1], v67, v67, 1.0
	v_rcp_f32_e32 v1, v0
	s_nop 0
	v_fma_f32 v2, -v0, v1, 1.0
	v_fmac_f32_e32 v1, v2, v1
	v_div_scale_f32 v2, vcc, 1.0, v67, 1.0
	v_mul_f32_e32 v16, v2, v1
	v_fma_f32 v17, -v0, v16, v2
	v_fmac_f32_e32 v16, v17, v1
	v_fma_f32 v0, -v0, v16, v2
	v_div_fmas_f32 v0, v0, v1, v16
	v_div_fixup_f32 v2, v0, v67, 1.0
	v_or_b32_e32 v0, 3, v68
	v_mad_u64_u32 v[16:17], s[0:1], v0, s33, v[70:71]
	v_add_u32_e32 v17, s6, v17
	v_lshl_add_u64 v[16:17], v[16:17], 0, s[84:85]
	v_lshl_add_u64 v[16:17], v[16:17], 0, v[176:177]
	v_lshl_add_u64 v[32:33], v[16:17], 0, s[2:3]
	v_add_co_u32_e32 v16, vcc, s63, v16
	v_mov_b32_e32 v1, v69
	s_nop 0
	v_addc_co_u32_e32 v17, vcc, 0, v17, vcc
	s_waitcnt vmcnt(28)
	v_mov_b32_e32 v16, v96
	v_mul_f32_e32 v17, v51, v2
	v_lshlrev_b64 v[0:1], 12, v[0:1]
	v_lshl_add_u64 v[0:1], s[82:83], 0, v[0:1]
	v_lshl_add_u64 v[0:1], v[0:1], 0, s[84:85]
	v_lshl_add_u64 v[0:1], v[0:1], 0, v[176:177]
	s_nop 0
	v_lshlrev_b32_e32 v16, 16, v16
	v_mul_f32_e32 v18, 0xbfb8aa3b, v16
	v_exp_f32_e32 v18, v18
	s_nop 0
	v_add_f32_e32 v18, 1.0, v18
	v_div_scale_f32 v34, s[0:1], v18, v18, v16
	v_rcp_f32_e32 v48, v34
	s_nop 0
	v_fma_f32 v49, -v34, v48, 1.0
	v_fmac_f32_e32 v48, v49, v48
	v_div_scale_f32 v49, vcc, v16, v18, v16
	v_mul_f32_e32 v50, v49, v48
	v_fma_f32 v51, -v34, v50, v49
	v_fmac_f32_e32 v50, v51, v48
	v_fma_f32 v34, -v34, v50, v49
	v_div_fmas_f32 v34, v34, v48, v50
	v_div_fixup_f32 v16, v34, v18, v16
	v_mul_f32_e32 v16, v17, v16
	v_cvt_pk_bf16_f32 v16, v16, s0
	global_store_short v[0:1], v16, off offset:3072
	s_waitcnt vmcnt(28)
; __device__ __forceinline__ int crow(int r, int hi) { return (r & 3) + 8 * (r >> 2) + 4 * hi; }
; __device__ __forceinline__ unsigned cvtpk(float lo, float hi) { f32x2_t v = {lo, hi}; bf16x2_t b = __builtin_convertvector(v, bf16x2_t); return __builtin_bit_cast(unsigned, b); }
; __device__ __forceinline__ float bf2f(unsigned short h) { return __uint_as_float(((unsigned)h) << 16); }
; __device__ __forceinline__ float silu(float x) { return x / (1.0f + __expf(-x)); }
; __device__ __forceinline__ void mem_unit(const MemArgs& A, int unit, char* lds, int wv) {
;     ...
;     if (hi == 0) wsl[r32] = l_reg;
;     asm volatile("s_waitcnt lgkmcnt(0)" ::: "memory");
; #pragma unroll
;     for (int r = 0; r < 16; ++r) { const int rr_ = crow(r, hi); const float rl = 1.0f / wsl[rr_];
;         const bf16* gp = A.proj + (grow0 + rr_) * INC + C_MG + hm * 128 + r32; bf16* yp = A.y + (grow0 + rr_) * DM + Y_M + hm * 128 + r32;
; #pragma unroll
;         for (int d0 = 0; d0 < 4; ++d0) { const float g = bf2f(gp[d0 * 32]); const float val = o[d0][r] * rl * silu(g);
;             yp[d0 * 32] = (bf16)(cvtpk(val, val) & 0xffffu); } }
;     __syncthreads();
	v_mov_b32_e32 v16, v97
	v_mul_f32_e32 v17, v35, v2
	s_nop 0
	v_lshlrev_b32_e32 v16, 16, v16
	v_mul_f32_e32 v18, 0xbfb8aa3b, v16
	v_exp_f32_e32 v18, v18
	s_nop 0
	v_add_f32_e32 v18, 1.0, v18
	v_div_scale_f32 v34, s[0:1], v18, v18, v16
	v_rcp_f32_e32 v35, v34
	s_nop 0
	v_fma_f32 v48, -v34, v35, 1.0
	v_fmac_f32_e32 v35, v48, v35
	v_div_scale_f32 v48, vcc, v16, v18, v16
	v_mul_f32_e32 v49, v48, v35
	v_fma_f32 v50, -v34, v49, v48
	v_fmac_f32_e32 v49, v50, v35
	v_fma_f32 v34, -v34, v49, v48
	v_div_fmas_f32 v34, v34, v35, v49
	v_div_fixup_f32 v16, v34, v18, v16
	v_mul_f32_e32 v16, v17, v16
	v_cvt_pk_bf16_f32 v16, v16, s0
	global_store_short v[0:1], v16, off offset:3136
	s_waitcnt vmcnt(28)
	v_mov_b32_e32 v16, v98
	v_mul_f32_e32 v17, v19, v2
	v_mul_f32_e32 v2, v3, v2
	s_nop 0
	v_lshlrev_b32_e32 v16, 16, v16
	v_mul_f32_e32 v18, 0xbfb8aa3b, v16
	v_exp_f32_e32 v18, v18
	s_nop 0
	v_add_f32_e32 v18, 1.0, v18
	v_div_scale_f32 v19, s[0:1], v18, v18, v16
	v_rcp_f32_e32 v34, v19
	s_nop 0
	v_fma_f32 v35, -v19, v34, 1.0
	v_fmac_f32_e32 v34, v35, v34
	v_div_scale_f32 v35, vcc, v16, v18, v16
	v_mul_f32_e32 v48, v35, v34
	v_fma_f32 v49, -v19, v48, v35
	v_fmac_f32_e32 v48, v49, v34
	v_fma_f32 v19, -v19, v48, v35
	v_div_fmas_f32 v19, v19, v34, v48
	v_div_fixup_f32 v16, v19, v18, v16
	v_mul_f32_e32 v16, v17, v16
	v_cvt_pk_bf16_f32 v16, v16, s0
	global_store_short v[0:1], v16, off offset:3200
	s_waitcnt vmcnt(28)
	v_mov_b32_e32 v16, v99
	s_nop 0
	v_lshlrev_b32_e32 v16, 16, v16
	v_mul_f32_e32 v3, 0xbfb8aa3b, v16
	v_exp_f32_e32 v3, v3
	s_nop 0
	v_add_f32_e32 v3, 1.0, v3
	v_div_scale_f32 v17, s[0:1], v3, v3, v16
	v_rcp_f32_e32 v18, v17
	s_nop 0
	v_fma_f32 v19, -v17, v18, 1.0
	v_fmac_f32_e32 v18, v19, v18
	v_div_scale_f32 v19, vcc, v16, v3, v16
	v_mul_f32_e32 v32, v19, v18
	v_fma_f32 v33, -v17, v32, v19
	v_fmac_f32_e32 v32, v33, v18
	v_fma_f32 v17, -v17, v32, v19
	v_div_fmas_f32 v17, v17, v18, v32
	v_div_fixup_f32 v3, v17, v3, v16
	v_mul_f32_e32 v2, v2, v3
	v_cvt_pk_bf16_f32 v2, v2, s0
	global_store_short v[0:1], v2, off offset:3264
	ds_read_b128 v[0:3], v72 offset:32
	s_waitcnt lgkmcnt(0)
	v_div_scale_f32 v16, s[0:1], v0, v0, 1.0
	v_rcp_f32_e32 v17, v16
	s_nop 0
	v_fma_f32 v18, -v16, v17, 1.0
	v_fmac_f32_e32 v17, v18, v17
	v_div_scale_f32 v18, vcc, 1.0, v0, 1.0
	v_mul_f32_e32 v19, v18, v17
	v_fma_f32 v32, -v16, v19, v18
	v_fmac_f32_e32 v19, v32, v17
	v_fma_f32 v16, -v16, v19, v18
	v_div_fmas_f32 v16, v16, v17, v19
	v_div_fixup_f32 v0, v16, v0, 1.0
	v_or_b32_e32 v16, 8, v68
	v_mad_u64_u32 v[18:19], s[0:1], v16, s33, v[70:71]
	v_add_u32_e32 v19, s6, v19
	v_lshl_add_u64 v[18:19], v[18:19], 0, s[84:85]
	v_lshl_add_u64 v[32:33], v[18:19], 0, v[176:177]
	v_lshl_add_u64 v[18:19], v[32:33], 0, s[2:3]
	v_add_co_u32_e32 v32, vcc, s63, v32
	v_mov_b32_e32 v17, v69
	s_nop 0
	v_addc_co_u32_e32 v33, vcc, 0, v33, vcc
	s_waitcnt vmcnt(28)
	v_mov_b32_e32 v32, v100
	v_lshlrev_b64 v[16:17], 12, v[16:17]
	v_lshl_add_u64 v[16:17], s[82:83], 0, v[16:17]
	v_mul_f32_e32 v33, v52, v0
	v_lshl_add_u64 v[16:17], v[16:17], 0, s[84:85]
	v_lshl_add_u64 v[16:17], v[16:17], 0, v[176:177]
	v_mul_f32_e32 v20, v20, v0
	s_nop 0
	v_lshlrev_b32_e32 v32, 16, v32
	v_mul_f32_e32 v34, 0xbfb8aa3b, v32
	v_exp_f32_e32 v34, v34
	s_nop 0
	v_add_f32_e32 v34, 1.0, v34
	v_div_scale_f32 v35, s[0:1], v34, v34, v32
	v_rcp_f32_e32 v48, v35
	s_nop 0
	v_fma_f32 v49, -v35, v48, 1.0
	v_fmac_f32_e32 v48, v49, v48
	v_div_scale_f32 v49, vcc, v32, v34, v32
	v_mul_f32_e32 v50, v49, v48
	v_fma_f32 v51, -v35, v50, v49
	v_fmac_f32_e32 v50, v51, v48
	v_fma_f32 v35, -v35, v50, v49
	v_div_fmas_f32 v35, v35, v48, v50
	v_div_fixup_f32 v32, v35, v34, v32
	v_mul_f32_e32 v32, v33, v32
	v_cvt_pk_bf16_f32 v32, v32, s0
	global_store_short v[16:17], v32, off offset:3072
	s_waitcnt vmcnt(28)
	v_mov_b32_e32 v32, v101
	v_mul_f32_e32 v33, v36, v0
	v_mul_f32_e32 v0, v4, v0
	s_nop 0
	v_lshlrev_b32_e32 v32, 16, v32
	v_mul_f32_e32 v34, 0xbfb8aa3b, v32
	v_exp_f32_e32 v34, v34
	s_nop 0
	v_add_f32_e32 v34, 1.0, v34
	v_div_scale_f32 v35, s[0:1], v34, v34, v32
	v_rcp_f32_e32 v36, v35
	s_nop 0
	v_fma_f32 v48, -v35, v36, 1.0
	v_fmac_f32_e32 v36, v48, v36
	v_div_scale_f32 v48, vcc, v32, v34, v32
	v_mul_f32_e32 v49, v48, v36
	v_fma_f32 v50, -v35, v49, v48
	v_fmac_f32_e32 v49, v50, v36
	v_fma_f32 v35, -v35, v49, v48
	v_div_fmas_f32 v35, v35, v36, v49
	v_div_fixup_f32 v32, v35, v34, v32
	v_mul_f32_e32 v32, v33, v32
	v_cvt_pk_bf16_f32 v32, v32, s0
	global_store_short v[16:17], v32, off offset:3136
	s_waitcnt vmcnt(28)
	v_mov_b32_e32 v32, v102
	s_nop 0
	v_lshlrev_b32_e32 v32, 16, v32
	s_waitcnt vmcnt(28)
	v_mov_b32_e32 v18, v103
	v_mul_f32_e32 v33, 0xbfb8aa3b, v32
	v_exp_f32_e32 v33, v33
	s_nop 0
	v_lshlrev_b32_e32 v18, 16, v18
	v_add_f32_e32 v33, 1.0, v33
	v_div_scale_f32 v34, s[0:1], v33, v33, v32
	v_rcp_f32_e32 v35, v34
	v_mul_f32_e32 v4, 0xbfb8aa3b, v18
	v_exp_f32_e32 v4, v4
	v_fma_f32 v36, -v34, v35, 1.0
	v_fmac_f32_e32 v35, v36, v35
	v_div_scale_f32 v36, vcc, v32, v33, v32
	v_mul_f32_e32 v48, v36, v35
	v_fma_f32 v49, -v34, v48, v36
	v_fmac_f32_e32 v48, v49, v35
	v_fma_f32 v34, -v34, v48, v36
	v_div_fmas_f32 v34, v34, v35, v48
	v_div_fixup_f32 v32, v34, v33, v32
	v_mul_f32_e32 v20, v20, v32
	v_add_f32_e32 v4, 1.0, v4
	v_cvt_pk_bf16_f32 v20, v20, s0
	v_div_scale_f32 v19, s[0:1], v4, v4, v18
	global_store_short v[16:17], v20, off offset:3200
	v_rcp_f32_e32 v20, v19
	s_nop 0
	v_fma_f32 v32, -v19, v20, 1.0
	v_fmac_f32_e32 v20, v32, v20
	v_div_scale_f32 v32, vcc, v18, v4, v18
	v_mul_f32_e32 v33, v32, v20
	v_fma_f32 v34, -v19, v33, v32
	v_fmac_f32_e32 v33, v34, v20
	v_fma_f32 v19, -v19, v33, v32
	v_div_fmas_f32 v19, v19, v20, v33
	v_div_fixup_f32 v4, v19, v4, v18
	v_mul_f32_e32 v0, v0, v4
	v_cvt_pk_bf16_f32 v0, v0, s0
	global_store_short v[16:17], v0, off offset:3264
	v_div_scale_f32 v0, s[0:1], v1, v1, 1.0
	v_rcp_f32_e32 v4, v0
	s_nop 0
	v_fma_f32 v16, -v0, v4, 1.0
	v_fmac_f32_e32 v4, v16, v4
	v_div_scale_f32 v16, vcc, 1.0, v1, 1.0
	v_mul_f32_e32 v17, v16, v4
	v_fma_f32 v18, -v0, v17, v16
	v_fmac_f32_e32 v17, v18, v4
	v_fma_f32 v0, -v0, v17, v16
	v_div_fmas_f32 v0, v0, v4, v17
	v_div_fixup_f32 v4, v0, v1, 1.0
	v_or_b32_e32 v0, 9, v68
	v_mad_u64_u32 v[16:17], s[0:1], v0, s33, v[70:71]
	v_add_u32_e32 v17, s6, v17
	v_lshl_add_u64 v[16:17], v[16:17], 0, s[84:85]
	v_lshl_add_u64 v[18:19], v[16:17], 0, v[176:177]
	v_lshl_add_u64 v[16:17], v[18:19], 0, s[2:3]
	v_add_co_u32_e32 v18, vcc, s63, v18
	v_mov_b32_e32 v1, v69
	s_nop 0
	v_addc_co_u32_e32 v19, vcc, 0, v19, vcc
	s_waitcnt vmcnt(28)
; __device__ __forceinline__ int crow(int r, int hi) { return (r & 3) + 8 * (r >> 2) + 4 * hi; }
; __device__ __forceinline__ unsigned cvtpk(float lo, float hi) { f32x2_t v = {lo, hi}; bf16x2_t b = __builtin_convertvector(v, bf16x2_t); return __builtin_bit_cast(unsigned, b); }
; __device__ __forceinline__ float bf2f(unsigned short h) { return __uint_as_float(((unsigned)h) << 16); }
; __device__ __forceinline__ float silu(float x) { return x / (1.0f + __expf(-x)); }
; __device__ __forceinline__ void mem_unit(const MemArgs& A, int unit, char* lds, int wv) {
;     ...
;     if (hi == 0) wsl[r32] = l_reg;
;     asm volatile("s_waitcnt lgkmcnt(0)" ::: "memory");
; #pragma unroll
;     for (int r = 0; r < 16; ++r) { const int rr_ = crow(r, hi); const float rl = 1.0f / wsl[rr_];
;         const bf16* gp = A.proj + (grow0 + rr_) * INC + C_MG + hm * 128 + r32; bf16* yp = A.y + (grow0 + rr_) * DM + Y_M + hm * 128 + r32;
; #pragma unroll
;         for (int d0 = 0; d0 < 4; ++d0) { const float g = bf2f(gp[d0 * 32]); const float val = o[d0][r] * rl * silu(g);
;             yp[d0 * 32] = (bf16)(cvtpk(val, val) & 0xffffu); } }
;     __syncthreads();
	v_mov_b32_e32 v18, v104
	v_lshlrev_b64 v[0:1], 12, v[0:1]
	v_lshl_add_u64 v[0:1], s[82:83], 0, v[0:1]
	v_mul_f32_e32 v19, v53, v4
	v_lshl_add_u64 v[0:1], v[0:1], 0, s[84:85]
	v_lshl_add_u64 v[0:1], v[0:1], 0, v[176:177]
	s_nop 0
	v_lshlrev_b32_e32 v18, 16, v18
	v_mul_f32_e32 v20, 0xbfb8aa3b, v18
	v_exp_f32_e32 v20, v20
	s_nop 0
	v_add_f32_e32 v20, 1.0, v20
	v_div_scale_f32 v32, s[0:1], v20, v20, v18
	v_rcp_f32_e32 v33, v32
	s_nop 0
	v_fma_f32 v34, -v32, v33, 1.0
	v_fmac_f32_e32 v33, v34, v33
	v_div_scale_f32 v34, vcc, v18, v20, v18
	v_mul_f32_e32 v35, v34, v33
	v_fma_f32 v36, -v32, v35, v34
	v_fmac_f32_e32 v35, v36, v33
	v_fma_f32 v32, -v32, v35, v34
	v_div_fmas_f32 v32, v32, v33, v35
	v_div_fixup_f32 v18, v32, v20, v18
	v_mul_f32_e32 v18, v19, v18
	v_cvt_pk_bf16_f32 v18, v18, s0
	global_store_short v[0:1], v18, off offset:3072
	s_waitcnt vmcnt(28)
	v_mov_b32_e32 v18, v105
	v_mul_f32_e32 v19, v37, v4
	s_nop 0
	v_lshlrev_b32_e32 v18, 16, v18
	v_mul_f32_e32 v20, 0xbfb8aa3b, v18
	v_exp_f32_e32 v20, v20
	s_nop 0
	v_add_f32_e32 v20, 1.0, v20
	v_div_scale_f32 v32, s[0:1], v20, v20, v18
	v_rcp_f32_e32 v33, v32
	s_nop 0
	v_fma_f32 v34, -v32, v33, 1.0
	v_fmac_f32_e32 v33, v34, v33
	v_div_scale_f32 v34, vcc, v18, v20, v18
	v_mul_f32_e32 v35, v34, v33
	v_fma_f32 v36, -v32, v35, v34
	v_fmac_f32_e32 v35, v36, v33
	v_fma_f32 v32, -v32, v35, v34
	v_div_fmas_f32 v32, v32, v33, v35
	v_div_fixup_f32 v18, v32, v20, v18
	v_mul_f32_e32 v18, v19, v18
	v_cvt_pk_bf16_f32 v18, v18, s0
	global_store_short v[0:1], v18, off offset:3136
	s_waitcnt vmcnt(28)
	v_mov_b32_e32 v18, v106
	v_mul_f32_e32 v19, v21, v4
	s_waitcnt vmcnt(28)
	v_mov_b32_e32 v16, v107
	v_mul_f32_e32 v4, v5, v4
	s_nop 0
	v_lshlrev_b32_e32 v18, 16, v18
	v_mul_f32_e32 v20, 0xbfb8aa3b, v18
	v_exp_f32_e32 v20, v20
	s_nop 0
	v_lshlrev_b32_e32 v16, 16, v16
	v_mul_f32_e32 v5, 0xbfb8aa3b, v16
	v_exp_f32_e32 v5, v5
	v_add_f32_e32 v20, 1.0, v20
	v_div_scale_f32 v21, s[0:1], v20, v20, v18
	v_rcp_f32_e32 v32, v21
	v_add_f32_e32 v5, 1.0, v5
	v_fma_f32 v33, -v21, v32, 1.0
	v_fmac_f32_e32 v32, v33, v32
	v_div_scale_f32 v33, vcc, v18, v20, v18
	v_mul_f32_e32 v34, v33, v32
	v_fma_f32 v35, -v21, v34, v33
	v_fmac_f32_e32 v34, v35, v32
	v_fma_f32 v21, -v21, v34, v33
	v_div_fmas_f32 v21, v21, v32, v34
	v_div_fixup_f32 v18, v21, v20, v18
	v_mul_f32_e32 v18, v19, v18
	v_cvt_pk_bf16_f32 v18, v18, s0
	v_div_scale_f32 v17, s[0:1], v5, v5, v16
	global_store_short v[0:1], v18, off offset:3200
	v_rcp_f32_e32 v18, v17
	s_nop 0
	v_fma_f32 v19, -v17, v18, 1.0
	v_fmac_f32_e32 v18, v19, v18
	v_div_scale_f32 v19, vcc, v16, v5, v16
	v_mul_f32_e32 v20, v19, v18
	v_fma_f32 v21, -v17, v20, v19
	v_fmac_f32_e32 v20, v21, v18
	v_fma_f32 v17, -v17, v20, v19
	v_div_fmas_f32 v17, v17, v18, v20
	v_div_fixup_f32 v5, v17, v5, v16
	v_mul_f32_e32 v4, v4, v5
	v_cvt_pk_bf16_f32 v4, v4, s0
	global_store_short v[0:1], v4, off offset:3264
	v_div_scale_f32 v0, s[0:1], v2, v2, 1.0
	v_rcp_f32_e32 v1, v0
	s_nop 0
	v_fma_f32 v4, -v0, v1, 1.0
	v_fmac_f32_e32 v1, v4, v1
	v_div_scale_f32 v4, vcc, 1.0, v2, 1.0
	v_mul_f32_e32 v5, v4, v1
	v_fma_f32 v16, -v0, v5, v4
	v_fmac_f32_e32 v5, v16, v1
	v_fma_f32 v0, -v0, v5, v4
	v_div_fmas_f32 v0, v0, v1, v5
	v_div_fixup_f32 v2, v0, v2, 1.0
	v_or_b32_e32 v0, 10, v68
	v_mad_u64_u32 v[4:5], s[0:1], v0, s33, v[70:71]
	v_add_u32_e32 v5, s6, v5
	v_lshl_add_u64 v[4:5], v[4:5], 0, s[84:85]
	v_lshl_add_u64 v[16:17], v[4:5], 0, v[176:177]
	v_lshl_add_u64 v[4:5], v[16:17], 0, s[2:3]
	v_add_co_u32_e32 v16, vcc, s63, v16
	v_mov_b32_e32 v1, v69
	s_nop 0
	v_addc_co_u32_e32 v17, vcc, 0, v17, vcc
	s_waitcnt vmcnt(28)
	v_mov_b32_e32 v16, v108
	v_lshlrev_b64 v[0:1], 12, v[0:1]
	v_lshl_add_u64 v[0:1], s[82:83], 0, v[0:1]
	v_mul_f32_e32 v17, v54, v2
	v_lshl_add_u64 v[0:1], v[0:1], 0, s[84:85]
	v_lshl_add_u64 v[0:1], v[0:1], 0, v[176:177]
	s_nop 0
	v_lshlrev_b32_e32 v16, 16, v16
	v_mul_f32_e32 v18, 0xbfb8aa3b, v16
	v_exp_f32_e32 v18, v18
	s_nop 0
	v_add_f32_e32 v18, 1.0, v18
	v_div_scale_f32 v19, s[0:1], v18, v18, v16
	v_rcp_f32_e32 v20, v19
	s_nop 0
	v_fma_f32 v21, -v19, v20, 1.0
	v_fmac_f32_e32 v20, v21, v20
	v_div_scale_f32 v21, vcc, v16, v18, v16
	v_mul_f32_e32 v32, v21, v20
	v_fma_f32 v33, -v19, v32, v21
	v_fmac_f32_e32 v32, v33, v20
	v_fma_f32 v19, -v19, v32, v21
	v_div_fmas_f32 v19, v19, v20, v32
	v_div_fixup_f32 v16, v19, v18, v16
	v_mul_f32_e32 v16, v17, v16
	v_cvt_pk_bf16_f32 v16, v16, s0
	global_store_short v[0:1], v16, off offset:3072
	s_waitcnt vmcnt(28)
	v_mov_b32_e32 v16, v109
	v_mul_f32_e32 v17, v38, v2
	s_nop 0
	v_lshlrev_b32_e32 v16, 16, v16
	v_mul_f32_e32 v18, 0xbfb8aa3b, v16
	v_exp_f32_e32 v18, v18
	s_nop 0
	v_add_f32_e32 v18, 1.0, v18
	v_div_scale_f32 v19, s[0:1], v18, v18, v16
	v_rcp_f32_e32 v20, v19
	s_nop 0
	v_fma_f32 v21, -v19, v20, 1.0
	v_fmac_f32_e32 v20, v21, v20
	v_div_scale_f32 v21, vcc, v16, v18, v16
	v_mul_f32_e32 v32, v21, v20
	v_fma_f32 v33, -v19, v32, v21
	v_fmac_f32_e32 v32, v33, v20
	v_fma_f32 v19, -v19, v32, v21
	v_div_fmas_f32 v19, v19, v20, v32
	v_div_fixup_f32 v16, v19, v18, v16
	v_mul_f32_e32 v16, v17, v16
	v_cvt_pk_bf16_f32 v16, v16, s0
	global_store_short v[0:1], v16, off offset:3136
	s_waitcnt vmcnt(28)
	v_mov_b32_e32 v16, v110
	v_mul_f32_e32 v17, v22, v2
	s_waitcnt vmcnt(28)
; __device__ __forceinline__ int crow(int r, int hi) { return (r & 3) + 8 * (r >> 2) + 4 * hi; }
; __device__ __forceinline__ unsigned cvtpk(float lo, float hi) { f32x2_t v = {lo, hi}; bf16x2_t b = __builtin_convertvector(v, bf16x2_t); return __builtin_bit_cast(unsigned, b); }
; __device__ __forceinline__ float bf2f(unsigned short h) { return __uint_as_float(((unsigned)h) << 16); }
; __device__ __forceinline__ float silu(float x) { return x / (1.0f + __expf(-x)); }
; __device__ __forceinline__ void mem_unit(const MemArgs& A, int unit, char* lds, int wv) {
;     ...
;     if (hi == 0) wsl[r32] = l_reg;
;     asm volatile("s_waitcnt lgkmcnt(0)" ::: "memory");
; #pragma unroll
;     for (int r = 0; r < 16; ++r) { const int rr_ = crow(r, hi); const float rl = 1.0f / wsl[rr_];
;         const bf16* gp = A.proj + (grow0 + rr_) * INC + C_MG + hm * 128 + r32; bf16* yp = A.y + (grow0 + rr_) * DM + Y_M + hm * 128 + r32;
; #pragma unroll
;         for (int d0 = 0; d0 < 4; ++d0) { const float g = bf2f(gp[d0 * 32]); const float val = o[d0][r] * rl * silu(g);
;             yp[d0 * 32] = (bf16)(cvtpk(val, val) & 0xffffu); } }
;     __syncthreads();
	v_mov_b32_e32 v4, v111
	v_mul_f32_e32 v2, v6, v2
	s_nop 0
	v_lshlrev_b32_e32 v16, 16, v16
	v_mul_f32_e32 v18, 0xbfb8aa3b, v16
	v_exp_f32_e32 v18, v18
	s_nop 0
	v_lshlrev_b32_e32 v4, 16, v4
	v_mul_f32_e32 v5, 0xbfb8aa3b, v4
	v_exp_f32_e32 v5, v5
	v_add_f32_e32 v18, 1.0, v18
	v_div_scale_f32 v19, s[0:1], v18, v18, v16
	v_rcp_f32_e32 v20, v19
	v_add_f32_e32 v5, 1.0, v5
	v_fma_f32 v21, -v19, v20, 1.0
	v_fmac_f32_e32 v20, v21, v20
	v_div_scale_f32 v21, vcc, v16, v18, v16
	v_mul_f32_e32 v22, v21, v20
	v_fma_f32 v32, -v19, v22, v21
	v_fmac_f32_e32 v22, v32, v20
	v_fma_f32 v19, -v19, v22, v21
	v_div_fmas_f32 v19, v19, v20, v22
	v_div_fixup_f32 v16, v19, v18, v16
	v_mul_f32_e32 v16, v17, v16
	v_cvt_pk_bf16_f32 v16, v16, s0
	v_div_scale_f32 v6, s[0:1], v5, v5, v4
	global_store_short v[0:1], v16, off offset:3200
	v_rcp_f32_e32 v16, v6
	s_nop 0
	v_fma_f32 v17, -v6, v16, 1.0
	v_fmac_f32_e32 v16, v17, v16
	v_div_scale_f32 v17, vcc, v4, v5, v4
	v_mul_f32_e32 v18, v17, v16
	v_fma_f32 v19, -v6, v18, v17
	v_fmac_f32_e32 v18, v19, v16
	v_fma_f32 v6, -v6, v18, v17
	v_div_fmas_f32 v6, v6, v16, v18
	v_div_fixup_f32 v4, v6, v5, v4
	v_mul_f32_e32 v2, v2, v4
	v_cvt_pk_bf16_f32 v2, v2, s0
	global_store_short v[0:1], v2, off offset:3264
	v_div_scale_f32 v0, s[0:1], v3, v3, 1.0
	v_rcp_f32_e32 v1, v0
	s_nop 0
	v_fma_f32 v2, -v0, v1, 1.0
	v_fmac_f32_e32 v1, v2, v1
	v_div_scale_f32 v2, vcc, 1.0, v3, 1.0
	v_mul_f32_e32 v4, v2, v1
	v_fma_f32 v5, -v0, v4, v2
	v_fmac_f32_e32 v4, v5, v1
	v_fma_f32 v0, -v0, v4, v2
	v_div_fmas_f32 v0, v0, v1, v4
	v_div_fixup_f32 v4, v0, v3, 1.0
	v_or_b32_e32 v0, 11, v68
	v_mad_u64_u32 v[2:3], s[0:1], v0, s33, v[70:71]
	v_add_u32_e32 v3, s6, v3
	v_lshl_add_u64 v[2:3], v[2:3], 0, s[84:85]
	v_lshl_add_u64 v[16:17], v[2:3], 0, v[176:177]
	v_lshl_add_u64 v[2:3], v[16:17], 0, s[2:3]
	v_add_co_u32_e32 v16, vcc, s63, v16
	v_mov_b32_e32 v1, v69
	s_nop 0
	v_addc_co_u32_e32 v17, vcc, 0, v17, vcc
	s_waitcnt vmcnt(28)
	v_mov_b32_e32 v5, v157
	v_lshlrev_b64 v[0:1], 12, v[0:1]
	v_lshl_add_u64 v[0:1], s[82:83], 0, v[0:1]
	v_mul_f32_e32 v6, v55, v4
	v_lshl_add_u64 v[0:1], v[0:1], 0, s[84:85]
	v_lshl_add_u64 v[0:1], v[0:1], 0, v[176:177]
	s_nop 0
	v_lshlrev_b32_e32 v5, 16, v5
	v_mul_f32_e32 v16, 0xbfb8aa3b, v5
	v_exp_f32_e32 v16, v16
	s_nop 0
	v_add_f32_e32 v16, 1.0, v16
	v_div_scale_f32 v17, s[0:1], v16, v16, v5
	v_rcp_f32_e32 v18, v17
	s_nop 0
	v_fma_f32 v19, -v17, v18, 1.0
	v_fmac_f32_e32 v18, v19, v18
	v_div_scale_f32 v19, vcc, v5, v16, v5
	v_mul_f32_e32 v20, v19, v18
	v_fma_f32 v21, -v17, v20, v19
	v_fmac_f32_e32 v20, v21, v18
	v_fma_f32 v17, -v17, v20, v19
	v_div_fmas_f32 v17, v17, v18, v20
	v_div_fixup_f32 v5, v17, v16, v5
	v_mul_f32_e32 v5, v6, v5
	v_cvt_pk_bf16_f32 v5, v5, s0
	global_store_short v[0:1], v5, off offset:3072
	s_waitcnt vmcnt(28)
	v_mov_b32_e32 v5, v158
	v_mul_f32_e32 v6, v39, v4
	s_nop 0
	v_lshlrev_b32_e32 v5, 16, v5
	v_mul_f32_e32 v16, 0xbfb8aa3b, v5
	v_exp_f32_e32 v16, v16
	s_nop 0
	v_add_f32_e32 v16, 1.0, v16
	v_div_scale_f32 v17, s[0:1], v16, v16, v5
	v_rcp_f32_e32 v18, v17
	s_nop 0
	v_fma_f32 v19, -v17, v18, 1.0
	v_fmac_f32_e32 v18, v19, v18
	v_div_scale_f32 v19, vcc, v5, v16, v5
	v_mul_f32_e32 v20, v19, v18
	v_fma_f32 v21, -v17, v20, v19
	v_fmac_f32_e32 v20, v21, v18
	v_fma_f32 v17, -v17, v20, v19
	v_div_fmas_f32 v17, v17, v18, v20
	v_div_fixup_f32 v5, v17, v16, v5
	v_mul_f32_e32 v5, v6, v5
	v_cvt_pk_bf16_f32 v5, v5, s0
	global_store_short v[0:1], v5, off offset:3136
	s_waitcnt vmcnt(28)
	v_mov_b32_e32 v5, v159
	v_mul_f32_e32 v6, v23, v4
	s_waitcnt vmcnt(28)
	v_mov_b32_e32 v2, v160
	v_mul_f32_e32 v3, v7, v4
	s_nop 0
	v_lshlrev_b32_e32 v5, 16, v5
	v_mul_f32_e32 v16, 0xbfb8aa3b, v5
	v_exp_f32_e32 v16, v16
	s_nop 0
	v_lshlrev_b32_e32 v2, 16, v2
	v_mul_f32_e32 v4, 0xbfb8aa3b, v2
	v_exp_f32_e32 v4, v4
	v_add_f32_e32 v16, 1.0, v16
	v_div_scale_f32 v17, s[0:1], v16, v16, v5
	v_rcp_f32_e32 v18, v17
	v_add_f32_e32 v4, 1.0, v4
	v_fma_f32 v19, -v17, v18, 1.0
	v_fmac_f32_e32 v18, v19, v18
	v_div_scale_f32 v19, vcc, v5, v16, v5
	v_mul_f32_e32 v20, v19, v18
	v_fma_f32 v21, -v17, v20, v19
	v_fmac_f32_e32 v20, v21, v18
	v_fma_f32 v17, -v17, v20, v19
	v_div_fmas_f32 v17, v17, v18, v20
	v_div_fixup_f32 v5, v17, v16, v5
	v_mul_f32_e32 v5, v6, v5
	v_cvt_pk_bf16_f32 v5, v5, s0
	global_store_short v[0:1], v5, off offset:3200
	v_div_scale_f32 v5, s[0:1], v4, v4, v2
	v_rcp_f32_e32 v6, v5
	s_nop 0
	v_fma_f32 v7, -v5, v6, 1.0
	v_fmac_f32_e32 v6, v7, v6
	v_div_scale_f32 v7, vcc, v2, v4, v2
	v_mul_f32_e32 v16, v7, v6
	v_fma_f32 v17, -v5, v16, v7
	v_fmac_f32_e32 v16, v17, v6
	v_fma_f32 v5, -v5, v16, v7
	v_div_fmas_f32 v5, v5, v6, v16
	v_div_fixup_f32 v2, v5, v4, v2
	v_mul_f32_e32 v2, v3, v2
	v_cvt_pk_bf16_f32 v2, v2, s0
	global_store_short v[0:1], v2, off offset:3264
	s_waitcnt vmcnt(16)
; __device__ __forceinline__ int crow(int r, int hi) { return (r & 3) + 8 * (r >> 2) + 4 * hi; }
; __device__ __forceinline__ unsigned cvtpk(float lo, float hi) { f32x2_t v = {lo, hi}; bf16x2_t b = __builtin_convertvector(v, bf16x2_t); return __builtin_bit_cast(unsigned, b); }
; __device__ __forceinline__ float bf2f(unsigned short h) { return __uint_as_float(((unsigned)h) << 16); }
; __device__ __forceinline__ float silu(float x) { return x / (1.0f + __expf(-x)); }
; __device__ __forceinline__ void mem_unit(const MemArgs& A, int unit, char* lds, int wv) {
;     ...
;     if (hi == 0) wsl[r32] = l_reg;
;     asm volatile("s_waitcnt lgkmcnt(0)" ::: "memory");
; #pragma unroll
;     for (int r = 0; r < 16; ++r) { const int rr_ = crow(r, hi); const float rl = 1.0f / wsl[rr_];
;         const bf16* gp = A.proj + (grow0 + rr_) * INC + C_MG + hm * 128 + r32; bf16* yp = A.y + (grow0 + rr_) * DM + Y_M + hm * 128 + r32;
; #pragma unroll
;         for (int d0 = 0; d0 < 4; ++d0) { const float g = bf2f(gp[d0 * 32]); const float val = o[d0][r] * rl * silu(g);
;             yp[d0 * 32] = (bf16)(cvtpk(val, val) & 0xffffu); } }
;     __syncthreads();
	v_add_u32_e32 v162, 0x38000, v161
	global_load_ushort v84, v162, s[80:81]
	global_load_ushort v85, v162, s[80:81] offset:64
	global_load_ushort v86, v162, s[80:81] offset:128
	global_load_ushort v87, v162, s[80:81] offset:192
	v_add_u32_e32 v163, 0x3b800, v161
	global_load_ushort v88, v163, s[80:81]
	global_load_ushort v89, v163, s[80:81] offset:64
	global_load_ushort v90, v163, s[80:81] offset:128
	global_load_ushort v91, v163, s[80:81] offset:192
	v_add_u32_e32 v162, 0x3f000, v161
	global_load_ushort v92, v162, s[80:81]
	global_load_ushort v93, v162, s[80:81] offset:64
	global_load_ushort v94, v162, s[80:81] offset:128
	global_load_ushort v95, v162, s[80:81] offset:192
	v_add_u32_e32 v163, 0x42800, v161
	global_load_ushort v96, v163, s[80:81]
	global_load_ushort v97, v163, s[80:81] offset:64
	global_load_ushort v98, v163, s[80:81] offset:128
	global_load_ushort v99, v163, s[80:81] offset:192
	v_add_u32_e32 v162, 0x54000, v161
	global_load_ushort v100, v162, s[80:81]
	global_load_ushort v101, v162, s[80:81] offset:64
	global_load_ushort v102, v162, s[80:81] offset:128
	global_load_ushort v103, v162, s[80:81] offset:192
	v_add_u32_e32 v163, 0x57800, v161
	global_load_ushort v104, v163, s[80:81]
	global_load_ushort v105, v163, s[80:81] offset:64
	global_load_ushort v106, v163, s[80:81] offset:128
	global_load_ushort v107, v163, s[80:81] offset:192
	v_add_u32_e32 v162, 0x5b000, v161
	global_load_ushort v108, v162, s[80:81]
	global_load_ushort v109, v162, s[80:81] offset:64
	global_load_ushort v110, v162, s[80:81] offset:128
	global_load_ushort v111, v162, s[80:81] offset:192
	v_add_u32_e32 v163, 0x5e800, v161
	global_load_ushort v157, v163, s[80:81]
	global_load_ushort v158, v163, s[80:81] offset:64
	global_load_ushort v159, v163, s[80:81] offset:128
	global_load_ushort v160, v163, s[80:81] offset:192
	ds_read_b128 v[0:3], v72 offset:64
	s_waitcnt lgkmcnt(0)
	v_div_scale_f32 v4, s[0:1], v0, v0, 1.0
	v_rcp_f32_e32 v5, v4
	s_nop 0
	v_fma_f32 v6, -v4, v5, 1.0
	v_fmac_f32_e32 v5, v6, v5
	v_div_scale_f32 v6, vcc, 1.0, v0, 1.0
	v_mul_f32_e32 v7, v6, v5
	v_fma_f32 v16, -v4, v7, v6
	v_fmac_f32_e32 v7, v16, v5
	v_fma_f32 v4, -v4, v7, v6
	v_div_fmas_f32 v4, v4, v5, v7
	v_div_fixup_f32 v0, v4, v0, 1.0
	v_or_b32_e32 v4, 16, v68
	v_mad_u64_u32 v[6:7], s[0:1], v4, s33, v[70:71]
	v_add_u32_e32 v7, s6, v7
	v_lshl_add_u64 v[6:7], v[6:7], 0, s[84:85]
	v_lshl_add_u64 v[16:17], v[6:7], 0, v[176:177]
	v_lshl_add_u64 v[6:7], v[16:17], 0, s[2:3]
	v_add_co_u32_e32 v16, vcc, s63, v16
	v_mov_b32_e32 v5, v69
	s_nop 0
	v_addc_co_u32_e32 v17, vcc, 0, v17, vcc
	s_waitcnt vmcnt(28)
	v_mov_b32_e32 v16, v84
	v_lshlrev_b64 v[4:5], 12, v[4:5]
	v_lshl_add_u64 v[4:5], s[82:83], 0, v[4:5]
	v_mul_f32_e32 v17, v56, v0
	v_lshl_add_u64 v[4:5], v[4:5], 0, s[84:85]
	v_lshl_add_u64 v[4:5], v[4:5], 0, v[176:177]
	s_nop 0
	v_lshlrev_b32_e32 v16, 16, v16
	v_mul_f32_e32 v18, 0xbfb8aa3b, v16
	v_exp_f32_e32 v18, v18
	s_nop 0
	v_add_f32_e32 v18, 1.0, v18
	v_div_scale_f32 v19, s[0:1], v18, v18, v16
	v_rcp_f32_e32 v20, v19
	s_nop 0
	v_fma_f32 v21, -v19, v20, 1.0
	v_fmac_f32_e32 v20, v21, v20
	v_div_scale_f32 v21, vcc, v16, v18, v16
	v_mul_f32_e32 v22, v21, v20
	v_fma_f32 v23, -v19, v22, v21
	v_fmac_f32_e32 v22, v23, v20
	v_fma_f32 v19, -v19, v22, v21
	v_div_fmas_f32 v19, v19, v20, v22
	v_div_fixup_f32 v16, v19, v18, v16
	v_mul_f32_e32 v16, v17, v16
	v_cvt_pk_bf16_f32 v16, v16, s0
	global_store_short v[4:5], v16, off offset:3072
	s_waitcnt vmcnt(28)
	v_mov_b32_e32 v16, v85
	v_mul_f32_e32 v17, v40, v0
	s_nop 0
	v_lshlrev_b32_e32 v16, 16, v16
	v_mul_f32_e32 v18, 0xbfb8aa3b, v16
	v_exp_f32_e32 v18, v18
	s_nop 0
	v_add_f32_e32 v18, 1.0, v18
	v_div_scale_f32 v19, s[0:1], v18, v18, v16
	v_rcp_f32_e32 v20, v19
	s_nop 0
	v_fma_f32 v21, -v19, v20, 1.0
	v_fmac_f32_e32 v20, v21, v20
	v_div_scale_f32 v21, vcc, v16, v18, v16
	v_mul_f32_e32 v22, v21, v20
	v_fma_f32 v23, -v19, v22, v21
	v_fmac_f32_e32 v22, v23, v20
	v_fma_f32 v19, -v19, v22, v21
	v_div_fmas_f32 v19, v19, v20, v22
	v_div_fixup_f32 v16, v19, v18, v16
	v_mul_f32_e32 v16, v17, v16
	v_cvt_pk_bf16_f32 v16, v16, s0
	global_store_short v[4:5], v16, off offset:3136
	s_waitcnt vmcnt(28)
	v_mov_b32_e32 v16, v86
	v_mul_f32_e32 v17, v24, v0
	s_waitcnt vmcnt(28)
	v_mov_b32_e32 v6, v87
	v_mul_f32_e32 v0, v8, v0
	s_nop 0
	v_lshlrev_b32_e32 v16, 16, v16
	v_mul_f32_e32 v18, 0xbfb8aa3b, v16
	v_exp_f32_e32 v18, v18
	s_nop 0
	v_lshlrev_b32_e32 v6, 16, v6
	v_mul_f32_e32 v7, 0xbfb8aa3b, v6
	v_exp_f32_e32 v7, v7
	v_add_f32_e32 v18, 1.0, v18
	v_div_scale_f32 v19, s[0:1], v18, v18, v16
	v_rcp_f32_e32 v20, v19
	v_add_f32_e32 v7, 1.0, v7
	v_fma_f32 v21, -v19, v20, 1.0
	v_fmac_f32_e32 v20, v21, v20
	v_div_scale_f32 v21, vcc, v16, v18, v16
	v_mul_f32_e32 v22, v21, v20
	v_fma_f32 v23, -v19, v22, v21
	v_fmac_f32_e32 v22, v23, v20
	v_fma_f32 v19, -v19, v22, v21
	v_div_fmas_f32 v19, v19, v20, v22
	v_div_fixup_f32 v16, v19, v18, v16
	v_mul_f32_e32 v16, v17, v16
	v_cvt_pk_bf16_f32 v16, v16, s0
	v_div_scale_f32 v8, s[0:1], v7, v7, v6
	global_store_short v[4:5], v16, off offset:3200
	v_rcp_f32_e32 v16, v8
	s_nop 0
	v_fma_f32 v17, -v8, v16, 1.0
	v_fmac_f32_e32 v16, v17, v16
	v_div_scale_f32 v17, vcc, v6, v7, v6
	v_mul_f32_e32 v18, v17, v16
	v_fma_f32 v19, -v8, v18, v17
	v_fmac_f32_e32 v18, v19, v16
	v_fma_f32 v8, -v8, v18, v17
	v_div_fmas_f32 v8, v8, v16, v18
	v_div_fixup_f32 v6, v8, v7, v6
	v_mul_f32_e32 v0, v0, v6
	v_cvt_pk_bf16_f32 v0, v0, s0
	global_store_short v[4:5], v0, off offset:3264
	v_div_scale_f32 v0, s[0:1], v1, v1, 1.0
	v_rcp_f32_e32 v4, v0
	s_nop 0
	v_fma_f32 v5, -v0, v4, 1.0
	v_fmac_f32_e32 v4, v5, v4
	v_div_scale_f32 v5, vcc, 1.0, v1, 1.0
	v_mul_f32_e32 v6, v5, v4
	v_fma_f32 v7, -v0, v6, v5
	v_fmac_f32_e32 v6, v7, v4
	v_fma_f32 v0, -v0, v6, v5
	v_div_fmas_f32 v0, v0, v4, v6
	v_div_fixup_f32 v8, v0, v1, 1.0
	v_or_b32_e32 v0, 17, v68
	v_mad_u64_u32 v[4:5], s[0:1], v0, s33, v[70:71]
	v_add_u32_e32 v5, s6, v5
	v_lshl_add_u64 v[4:5], v[4:5], 0, s[84:85]
	v_lshl_add_u64 v[4:5], v[4:5], 0, v[176:177]
	v_lshl_add_u64 v[6:7], v[4:5], 0, s[2:3]
	v_add_co_u32_e32 v4, vcc, s63, v4
	v_mov_b32_e32 v1, v69
	s_nop 0
	v_addc_co_u32_e32 v5, vcc, 0, v5, vcc
	s_waitcnt vmcnt(28)
; __device__ __forceinline__ int crow(int r, int hi) { return (r & 3) + 8 * (r >> 2) + 4 * hi; }
; __device__ __forceinline__ unsigned cvtpk(float lo, float hi) { f32x2_t v = {lo, hi}; bf16x2_t b = __builtin_convertvector(v, bf16x2_t); return __builtin_bit_cast(unsigned, b); }
; __device__ __forceinline__ float bf2f(unsigned short h) { return __uint_as_float(((unsigned)h) << 16); }
; __device__ __forceinline__ float silu(float x) { return x / (1.0f + __expf(-x)); }
; __device__ __forceinline__ void mem_unit(const MemArgs& A, int unit, char* lds, int wv) {
;     ...
;     if (hi == 0) wsl[r32] = l_reg;
;     asm volatile("s_waitcnt lgkmcnt(0)" ::: "memory");
; #pragma unroll
;     for (int r = 0; r < 16; ++r) { const int rr_ = crow(r, hi); const float rl = 1.0f / wsl[rr_];
;         const bf16* gp = A.proj + (grow0 + rr_) * INC + C_MG + hm * 128 + r32; bf16* yp = A.y + (grow0 + rr_) * DM + Y_M + hm * 128 + r32;
; #pragma unroll
;         for (int d0 = 0; d0 < 4; ++d0) { const float g = bf2f(gp[d0 * 32]); const float val = o[d0][r] * rl * silu(g);
;             yp[d0 * 32] = (bf16)(cvtpk(val, val) & 0xffffu); } }
;     __syncthreads();
	v_mov_b32_e32 v4, v88
	v_lshlrev_b64 v[0:1], 12, v[0:1]
	v_lshl_add_u64 v[0:1], s[82:83], 0, v[0:1]
	v_mul_f32_e32 v5, v57, v8
	v_lshl_add_u64 v[0:1], v[0:1], 0, s[84:85]
	v_lshl_add_u64 v[0:1], v[0:1], 0, v[176:177]
	s_nop 0
	v_lshlrev_b32_e32 v4, 16, v4
	v_mul_f32_e32 v16, 0xbfb8aa3b, v4
	v_exp_f32_e32 v16, v16
	s_nop 0
	v_add_f32_e32 v16, 1.0, v16
	v_div_scale_f32 v17, s[0:1], v16, v16, v4
	v_rcp_f32_e32 v18, v17
	s_nop 0
	v_fma_f32 v19, -v17, v18, 1.0
	v_fmac_f32_e32 v18, v19, v18
	v_div_scale_f32 v19, vcc, v4, v16, v4
	v_mul_f32_e32 v20, v19, v18
	v_fma_f32 v21, -v17, v20, v19
	v_fmac_f32_e32 v20, v21, v18
	v_fma_f32 v17, -v17, v20, v19
	v_div_fmas_f32 v17, v17, v18, v20
	v_div_fixup_f32 v4, v17, v16, v4
	v_mul_f32_e32 v4, v5, v4
	v_cvt_pk_bf16_f32 v4, v4, s0
	global_store_short v[0:1], v4, off offset:3072
	s_waitcnt vmcnt(28)
	v_mov_b32_e32 v4, v89
	v_mul_f32_e32 v5, v41, v8
	s_nop 0
	v_lshlrev_b32_e32 v4, 16, v4
	v_mul_f32_e32 v16, 0xbfb8aa3b, v4
	v_exp_f32_e32 v16, v16
	s_nop 0
	v_add_f32_e32 v16, 1.0, v16
	v_div_scale_f32 v17, s[0:1], v16, v16, v4
	v_rcp_f32_e32 v18, v17
	s_nop 0
	v_fma_f32 v19, -v17, v18, 1.0
	v_fmac_f32_e32 v18, v19, v18
	v_div_scale_f32 v19, vcc, v4, v16, v4
	v_mul_f32_e32 v20, v19, v18
	v_fma_f32 v21, -v17, v20, v19
	v_fmac_f32_e32 v20, v21, v18
	v_fma_f32 v17, -v17, v20, v19
	v_div_fmas_f32 v17, v17, v18, v20
	v_div_fixup_f32 v4, v17, v16, v4
	v_mul_f32_e32 v4, v5, v4
	v_cvt_pk_bf16_f32 v4, v4, s0
	global_store_short v[0:1], v4, off offset:3136
	s_waitcnt vmcnt(28)
	v_mov_b32_e32 v4, v90
	v_mul_f32_e32 v5, v25, v8
	s_nop 0
	v_lshlrev_b32_e32 v4, 16, v4
	v_mul_f32_e32 v16, 0xbfb8aa3b, v4
	v_exp_f32_e32 v16, v16
	s_nop 0
	v_add_f32_e32 v16, 1.0, v16
	v_div_scale_f32 v17, s[0:1], v16, v16, v4
	v_rcp_f32_e32 v18, v17
	s_nop 0
	v_fma_f32 v19, -v17, v18, 1.0
	v_fmac_f32_e32 v18, v19, v18
	v_div_scale_f32 v19, vcc, v4, v16, v4
	v_mul_f32_e32 v20, v19, v18
	v_fma_f32 v21, -v17, v20, v19
	v_fmac_f32_e32 v20, v21, v18
	v_fma_f32 v17, -v17, v20, v19
	v_div_fmas_f32 v17, v17, v18, v20
	v_div_fixup_f32 v4, v17, v16, v4
	v_mul_f32_e32 v4, v5, v4
	v_cvt_pk_bf16_f32 v4, v4, s0
	global_store_short v[0:1], v4, off offset:3200
	s_waitcnt vmcnt(28)
	v_mov_b32_e32 v4, v91
	v_mul_f32_e32 v5, v9, v8
	s_nop 0
	v_lshlrev_b32_e32 v4, 16, v4
	v_mul_f32_e32 v6, 0xbfb8aa3b, v4
	v_exp_f32_e32 v6, v6
	s_nop 0
	v_add_f32_e32 v6, 1.0, v6
	v_div_scale_f32 v7, s[0:1], v6, v6, v4
	v_rcp_f32_e32 v8, v7
	s_nop 0
	v_fma_f32 v9, -v7, v8, 1.0
	v_fmac_f32_e32 v8, v9, v8
	v_div_scale_f32 v9, vcc, v4, v6, v4
	v_mul_f32_e32 v16, v9, v8
	v_fma_f32 v17, -v7, v16, v9
	v_fmac_f32_e32 v16, v17, v8
	v_fma_f32 v7, -v7, v16, v9
	v_div_fmas_f32 v7, v7, v8, v16
	v_div_fixup_f32 v4, v7, v6, v4
	v_mul_f32_e32 v4, v5, v4
	v_cvt_pk_bf16_f32 v4, v4, s0
	global_store_short v[0:1], v4, off offset:3264
	v_div_scale_f32 v0, s[0:1], v2, v2, 1.0
	v_rcp_f32_e32 v1, v0
	s_nop 0
	v_fma_f32 v4, -v0, v1, 1.0
	v_fmac_f32_e32 v1, v4, v1
	v_div_scale_f32 v4, vcc, 1.0, v2, 1.0
	v_mul_f32_e32 v5, v4, v1
	v_fma_f32 v6, -v0, v5, v4
	v_fmac_f32_e32 v5, v6, v1
	v_fma_f32 v0, -v0, v5, v4
	v_div_fmas_f32 v0, v0, v1, v5
	v_div_fixup_f32 v2, v0, v2, 1.0
	v_or_b32_e32 v0, 18, v68
	v_mad_u64_u32 v[4:5], s[0:1], v0, s33, v[70:71]
	v_add_u32_e32 v5, s6, v5
	v_lshl_add_u64 v[4:5], v[4:5], 0, s[84:85]
	v_lshl_add_u64 v[4:5], v[4:5], 0, v[176:177]
	v_lshl_add_u64 v[6:7], v[4:5], 0, s[2:3]
	v_add_co_u32_e32 v4, vcc, s63, v4
	v_mov_b32_e32 v1, v69
	s_nop 0
	v_addc_co_u32_e32 v5, vcc, 0, v5, vcc
	s_waitcnt vmcnt(28)
	v_mov_b32_e32 v4, v92
	v_lshlrev_b64 v[0:1], 12, v[0:1]
	v_lshl_add_u64 v[0:1], s[82:83], 0, v[0:1]
	v_mul_f32_e32 v5, v58, v2
	v_lshl_add_u64 v[0:1], v[0:1], 0, s[84:85]
	v_lshl_add_u64 v[0:1], v[0:1], 0, v[176:177]
	s_nop 0
	v_lshlrev_b32_e32 v4, 16, v4
	v_mul_f32_e32 v8, 0xbfb8aa3b, v4
	v_exp_f32_e32 v8, v8
	s_nop 0
	v_add_f32_e32 v8, 1.0, v8
	v_div_scale_f32 v9, s[0:1], v8, v8, v4
	v_rcp_f32_e32 v16, v9
	s_nop 0
	v_fma_f32 v17, -v9, v16, 1.0
	v_fmac_f32_e32 v16, v17, v16
	v_div_scale_f32 v17, vcc, v4, v8, v4
	v_mul_f32_e32 v18, v17, v16
	v_fma_f32 v19, -v9, v18, v17
	v_fmac_f32_e32 v18, v19, v16
	v_fma_f32 v9, -v9, v18, v17
	v_div_fmas_f32 v9, v9, v16, v18
	v_div_fixup_f32 v4, v9, v8, v4
	v_mul_f32_e32 v4, v5, v4
	v_cvt_pk_bf16_f32 v4, v4, s0
	global_store_short v[0:1], v4, off offset:3072
	s_waitcnt vmcnt(28)
	v_mov_b32_e32 v4, v93
	v_mul_f32_e32 v5, v42, v2
	s_nop 0
	v_lshlrev_b32_e32 v4, 16, v4
	v_mul_f32_e32 v8, 0xbfb8aa3b, v4
	v_exp_f32_e32 v8, v8
	s_nop 0
	v_add_f32_e32 v8, 1.0, v8
	v_div_scale_f32 v9, s[0:1], v8, v8, v4
	v_rcp_f32_e32 v16, v9
	s_nop 0
	v_fma_f32 v17, -v9, v16, 1.0
	v_fmac_f32_e32 v16, v17, v16
	v_div_scale_f32 v17, vcc, v4, v8, v4
	v_mul_f32_e32 v18, v17, v16
	v_fma_f32 v19, -v9, v18, v17
	v_fmac_f32_e32 v18, v19, v16
	v_fma_f32 v9, -v9, v18, v17
	v_div_fmas_f32 v9, v9, v16, v18
	v_div_fixup_f32 v4, v9, v8, v4
	v_mul_f32_e32 v4, v5, v4
	v_cvt_pk_bf16_f32 v4, v4, s0
	global_store_short v[0:1], v4, off offset:3136
	s_waitcnt vmcnt(28)
	v_mov_b32_e32 v4, v94
	v_mul_f32_e32 v5, v26, v2
	v_mul_f32_e32 v2, v10, v2
	s_nop 0
	v_lshlrev_b32_e32 v4, 16, v4
	v_mul_f32_e32 v8, 0xbfb8aa3b, v4
	v_exp_f32_e32 v8, v8
	s_nop 0
	v_add_f32_e32 v8, 1.0, v8
	v_div_scale_f32 v9, s[0:1], v8, v8, v4
	v_rcp_f32_e32 v16, v9
	s_nop 0
	v_fma_f32 v17, -v9, v16, 1.0
	v_fmac_f32_e32 v16, v17, v16
	v_div_scale_f32 v17, vcc, v4, v8, v4
	v_mul_f32_e32 v18, v17, v16
	v_fma_f32 v19, -v9, v18, v17
	v_fmac_f32_e32 v18, v19, v16
	v_fma_f32 v9, -v9, v18, v17
	v_div_fmas_f32 v9, v9, v16, v18
	v_div_fixup_f32 v4, v9, v8, v4
	v_mul_f32_e32 v4, v5, v4
	v_cvt_pk_bf16_f32 v4, v4, s0
	global_store_short v[0:1], v4, off offset:3200
	s_waitcnt vmcnt(28)
; __device__ __forceinline__ int crow(int r, int hi) { return (r & 3) + 8 * (r >> 2) + 4 * hi; }
; __device__ __forceinline__ unsigned cvtpk(float lo, float hi) { f32x2_t v = {lo, hi}; bf16x2_t b = __builtin_convertvector(v, bf16x2_t); return __builtin_bit_cast(unsigned, b); }
; __device__ __forceinline__ float bf2f(unsigned short h) { return __uint_as_float(((unsigned)h) << 16); }
; __device__ __forceinline__ float silu(float x) { return x / (1.0f + __expf(-x)); }
; __device__ __forceinline__ void mem_unit(const MemArgs& A, int unit, char* lds, int wv) {
;     ...
;     if (hi == 0) wsl[r32] = l_reg;
;     asm volatile("s_waitcnt lgkmcnt(0)" ::: "memory");
; #pragma unroll
;     for (int r = 0; r < 16; ++r) { const int rr_ = crow(r, hi); const float rl = 1.0f / wsl[rr_];
;         const bf16* gp = A.proj + (grow0 + rr_) * INC + C_MG + hm * 128 + r32; bf16* yp = A.y + (grow0 + rr_) * DM + Y_M + hm * 128 + r32;
; #pragma unroll
;         for (int d0 = 0; d0 < 4; ++d0) { const float g = bf2f(gp[d0 * 32]); const float val = o[d0][r] * rl * silu(g);
;             yp[d0 * 32] = (bf16)(cvtpk(val, val) & 0xffffu); } }
;     __syncthreads();
	v_mov_b32_e32 v4, v95
	s_nop 0
	v_lshlrev_b32_e32 v4, 16, v4
	v_mul_f32_e32 v5, 0xbfb8aa3b, v4
	v_exp_f32_e32 v5, v5
	s_nop 0
	v_add_f32_e32 v5, 1.0, v5
	v_div_scale_f32 v6, s[0:1], v5, v5, v4
	v_rcp_f32_e32 v7, v6
	s_nop 0
	v_fma_f32 v8, -v6, v7, 1.0
	v_fmac_f32_e32 v7, v8, v7
	v_div_scale_f32 v8, vcc, v4, v5, v4
	v_mul_f32_e32 v9, v8, v7
	v_fma_f32 v10, -v6, v9, v8
	v_fmac_f32_e32 v9, v10, v7
	v_fma_f32 v6, -v6, v9, v8
	v_div_fmas_f32 v6, v6, v7, v9
	v_div_fixup_f32 v4, v6, v5, v4
	v_mul_f32_e32 v2, v2, v4
	v_cvt_pk_bf16_f32 v2, v2, s0
	global_store_short v[0:1], v2, off offset:3264
	v_div_scale_f32 v0, s[0:1], v3, v3, 1.0
	v_rcp_f32_e32 v1, v0
	s_nop 0
	v_fma_f32 v2, -v0, v1, 1.0
	v_fmac_f32_e32 v1, v2, v1
	v_div_scale_f32 v2, vcc, 1.0, v3, 1.0
	v_mul_f32_e32 v4, v2, v1
	v_fma_f32 v5, -v0, v4, v2
	v_fmac_f32_e32 v4, v5, v1
	v_fma_f32 v0, -v0, v4, v2
	v_div_fmas_f32 v0, v0, v1, v4
	v_div_fixup_f32 v6, v0, v3, 1.0
	v_or_b32_e32 v0, 19, v68
	v_mad_u64_u32 v[2:3], s[0:1], v0, s33, v[70:71]
	v_add_u32_e32 v3, s6, v3
	v_lshl_add_u64 v[2:3], v[2:3], 0, s[84:85]
	v_lshl_add_u64 v[2:3], v[2:3], 0, v[176:177]
	v_lshl_add_u64 v[4:5], v[2:3], 0, s[2:3]
	v_add_co_u32_e32 v2, vcc, s63, v2
	v_mov_b32_e32 v1, v69
	s_nop 0
	v_addc_co_u32_e32 v3, vcc, 0, v3, vcc
	s_waitcnt vmcnt(28)
	v_mov_b32_e32 v2, v96
	v_lshlrev_b64 v[0:1], 12, v[0:1]
	v_lshl_add_u64 v[0:1], s[82:83], 0, v[0:1]
	v_mul_f32_e32 v3, v59, v6
	v_lshl_add_u64 v[0:1], v[0:1], 0, s[84:85]
	v_lshl_add_u64 v[0:1], v[0:1], 0, v[176:177]
	s_nop 0
	v_lshlrev_b32_e32 v2, 16, v2
	v_mul_f32_e32 v7, 0xbfb8aa3b, v2
	v_exp_f32_e32 v7, v7
	s_nop 0
	v_add_f32_e32 v7, 1.0, v7
	v_div_scale_f32 v8, s[0:1], v7, v7, v2
	v_rcp_f32_e32 v9, v8
	s_nop 0
	v_fma_f32 v10, -v8, v9, 1.0
	v_fmac_f32_e32 v9, v10, v9
	v_div_scale_f32 v10, vcc, v2, v7, v2
	v_mul_f32_e32 v16, v10, v9
	v_fma_f32 v17, -v8, v16, v10
	v_fmac_f32_e32 v16, v17, v9
	v_fma_f32 v8, -v8, v16, v10
	v_div_fmas_f32 v8, v8, v9, v16
	v_div_fixup_f32 v2, v8, v7, v2
	v_mul_f32_e32 v2, v3, v2
	v_cvt_pk_bf16_f32 v2, v2, s0
	global_store_short v[0:1], v2, off offset:3072
	s_waitcnt vmcnt(28)
	v_mov_b32_e32 v2, v97
	v_mul_f32_e32 v3, v43, v6
	s_nop 0
	v_lshlrev_b32_e32 v2, 16, v2
	v_mul_f32_e32 v7, 0xbfb8aa3b, v2
	v_exp_f32_e32 v7, v7
	s_nop 0
	v_add_f32_e32 v7, 1.0, v7
	v_div_scale_f32 v8, s[0:1], v7, v7, v2
	v_rcp_f32_e32 v9, v8
	s_nop 0
	v_fma_f32 v10, -v8, v9, 1.0
	v_fmac_f32_e32 v9, v10, v9
	v_div_scale_f32 v10, vcc, v2, v7, v2
	v_mul_f32_e32 v16, v10, v9
	v_fma_f32 v17, -v8, v16, v10
	v_fmac_f32_e32 v16, v17, v9
	v_fma_f32 v8, -v8, v16, v10
	v_div_fmas_f32 v8, v8, v9, v16
	v_div_fixup_f32 v2, v8, v7, v2
	v_mul_f32_e32 v2, v3, v2
	v_cvt_pk_bf16_f32 v2, v2, s0
	global_store_short v[0:1], v2, off offset:3136
	s_waitcnt vmcnt(28)
	v_mov_b32_e32 v2, v98
	v_mul_f32_e32 v3, v27, v6
	s_nop 0
	v_lshlrev_b32_e32 v2, 16, v2
	v_mul_f32_e32 v7, 0xbfb8aa3b, v2
	v_exp_f32_e32 v7, v7
	s_nop 0
	v_add_f32_e32 v7, 1.0, v7
	v_div_scale_f32 v8, s[0:1], v7, v7, v2
	v_rcp_f32_e32 v9, v8
	s_nop 0
	v_fma_f32 v10, -v8, v9, 1.0
	v_fmac_f32_e32 v9, v10, v9
	v_div_scale_f32 v10, vcc, v2, v7, v2
	v_mul_f32_e32 v16, v10, v9
	v_fma_f32 v17, -v8, v16, v10
	v_fmac_f32_e32 v16, v17, v9
	v_fma_f32 v8, -v8, v16, v10
	v_div_fmas_f32 v8, v8, v9, v16
	v_div_fixup_f32 v2, v8, v7, v2
	v_mul_f32_e32 v2, v3, v2
	v_cvt_pk_bf16_f32 v2, v2, s0
	global_store_short v[0:1], v2, off offset:3200
	s_waitcnt vmcnt(28)
	v_mov_b32_e32 v2, v99
	v_mul_f32_e32 v3, v11, v6
	s_nop 0
	v_lshlrev_b32_e32 v2, 16, v2
	v_mul_f32_e32 v4, 0xbfb8aa3b, v2
	v_exp_f32_e32 v4, v4
	s_nop 0
	v_add_f32_e32 v4, 1.0, v4
	v_div_scale_f32 v5, s[0:1], v4, v4, v2
	v_rcp_f32_e32 v6, v5
	s_nop 0
	v_fma_f32 v7, -v5, v6, 1.0
	v_fmac_f32_e32 v6, v7, v6
	v_div_scale_f32 v7, vcc, v2, v4, v2
	v_mul_f32_e32 v8, v7, v6
	v_fma_f32 v9, -v5, v8, v7
	v_fmac_f32_e32 v8, v9, v6
	v_fma_f32 v5, -v5, v8, v7
	v_div_fmas_f32 v5, v5, v6, v8
	v_div_fixup_f32 v2, v5, v4, v2
	v_mul_f32_e32 v2, v3, v2
	v_cvt_pk_bf16_f32 v2, v2, s0
	global_store_short v[0:1], v2, off offset:3264
	ds_read_b128 v[0:3], v72 offset:96
	s_waitcnt lgkmcnt(0)
	v_div_scale_f32 v4, s[0:1], v0, v0, 1.0
	v_rcp_f32_e32 v5, v4
	s_nop 0
	v_fma_f32 v6, -v4, v5, 1.0
	v_fmac_f32_e32 v5, v6, v5
	v_div_scale_f32 v6, vcc, 1.0, v0, 1.0
	v_mul_f32_e32 v7, v6, v5
	v_fma_f32 v8, -v4, v7, v6
	v_fmac_f32_e32 v7, v8, v5
	v_fma_f32 v4, -v4, v7, v6
	v_div_fmas_f32 v4, v4, v5, v7
	v_div_fixup_f32 v0, v4, v0, 1.0
	v_or_b32_e32 v4, 24, v68
	v_mad_u64_u32 v[6:7], s[0:1], v4, s33, v[70:71]
	v_add_u32_e32 v7, s6, v7
	v_lshl_add_u64 v[6:7], v[6:7], 0, s[84:85]
	v_lshl_add_u64 v[8:9], v[6:7], 0, v[176:177]
	v_lshl_add_u64 v[6:7], v[8:9], 0, s[2:3]
	v_add_co_u32_e32 v8, vcc, s63, v8
	v_mov_b32_e32 v5, v69
	s_nop 0
	v_addc_co_u32_e32 v9, vcc, 0, v9, vcc
	s_waitcnt vmcnt(28)
	v_mov_b32_e32 v8, v100
	v_lshlrev_b64 v[4:5], 12, v[4:5]
	v_lshl_add_u64 v[4:5], s[82:83], 0, v[4:5]
	v_mul_f32_e32 v9, v60, v0
	v_lshl_add_u64 v[4:5], v[4:5], 0, s[84:85]
	v_lshl_add_u64 v[4:5], v[4:5], 0, v[176:177]
	s_nop 0
	v_lshlrev_b32_e32 v8, 16, v8
	v_mul_f32_e32 v10, 0xbfb8aa3b, v8
	v_exp_f32_e32 v10, v10
	s_nop 0
	v_add_f32_e32 v10, 1.0, v10
	v_div_scale_f32 v11, s[0:1], v10, v10, v8
	v_rcp_f32_e32 v16, v11
	s_nop 0
	v_fma_f32 v17, -v11, v16, 1.0
	v_fmac_f32_e32 v16, v17, v16
	v_div_scale_f32 v17, vcc, v8, v10, v8
	v_mul_f32_e32 v18, v17, v16
	v_fma_f32 v19, -v11, v18, v17
	v_fmac_f32_e32 v18, v19, v16
	v_fma_f32 v11, -v11, v18, v17
	v_div_fmas_f32 v11, v11, v16, v18
	v_div_fixup_f32 v8, v11, v10, v8
	v_mul_f32_e32 v8, v9, v8
	v_cvt_pk_bf16_f32 v8, v8, s0
	global_store_short v[4:5], v8, off offset:3072
	s_waitcnt vmcnt(28)
; __device__ __forceinline__ int crow(int r, int hi) { return (r & 3) + 8 * (r >> 2) + 4 * hi; }
; __device__ __forceinline__ unsigned cvtpk(float lo, float hi) { f32x2_t v = {lo, hi}; bf16x2_t b = __builtin_convertvector(v, bf16x2_t); return __builtin_bit_cast(unsigned, b); }
; __device__ __forceinline__ float bf2f(unsigned short h) { return __uint_as_float(((unsigned)h) << 16); }
; __device__ __forceinline__ float silu(float x) { return x / (1.0f + __expf(-x)); }
; __device__ __forceinline__ void mem_unit(const MemArgs& A, int unit, char* lds, int wv) {
;     ...
;     if (hi == 0) wsl[r32] = l_reg;
;     asm volatile("s_waitcnt lgkmcnt(0)" ::: "memory");
; #pragma unroll
;     for (int r = 0; r < 16; ++r) { const int rr_ = crow(r, hi); const float rl = 1.0f / wsl[rr_];
;         const bf16* gp = A.proj + (grow0 + rr_) * INC + C_MG + hm * 128 + r32; bf16* yp = A.y + (grow0 + rr_) * DM + Y_M + hm * 128 + r32;
; #pragma unroll
;         for (int d0 = 0; d0 < 4; ++d0) { const float g = bf2f(gp[d0 * 32]); const float val = o[d0][r] * rl * silu(g);
;             yp[d0 * 32] = (bf16)(cvtpk(val, val) & 0xffffu); } }
;     __syncthreads();
	v_mov_b32_e32 v8, v101
	v_mul_f32_e32 v9, v44, v0
	s_nop 0
	v_lshlrev_b32_e32 v8, 16, v8
	v_mul_f32_e32 v10, 0xbfb8aa3b, v8
	v_exp_f32_e32 v10, v10
	s_nop 0
	v_add_f32_e32 v10, 1.0, v10
	v_div_scale_f32 v11, s[0:1], v10, v10, v8
	v_rcp_f32_e32 v16, v11
	s_nop 0
	v_fma_f32 v17, -v11, v16, 1.0
	v_fmac_f32_e32 v16, v17, v16
	v_div_scale_f32 v17, vcc, v8, v10, v8
	v_mul_f32_e32 v18, v17, v16
	v_fma_f32 v19, -v11, v18, v17
	v_fmac_f32_e32 v18, v19, v16
	v_fma_f32 v11, -v11, v18, v17
	v_div_fmas_f32 v11, v11, v16, v18
	v_div_fixup_f32 v8, v11, v10, v8
	v_mul_f32_e32 v8, v9, v8
	v_cvt_pk_bf16_f32 v8, v8, s0
	global_store_short v[4:5], v8, off offset:3136
	s_waitcnt vmcnt(28)
	v_mov_b32_e32 v8, v102
	v_mul_f32_e32 v9, v28, v0
	s_waitcnt vmcnt(28)
	v_mov_b32_e32 v6, v103
	v_mul_f32_e32 v0, v12, v0
	s_nop 0
	v_lshlrev_b32_e32 v8, 16, v8
	v_mul_f32_e32 v10, 0xbfb8aa3b, v8
	v_exp_f32_e32 v10, v10
	s_nop 0
	v_lshlrev_b32_e32 v6, 16, v6
	v_mul_f32_e32 v7, 0xbfb8aa3b, v6
	v_exp_f32_e32 v7, v7
	v_add_f32_e32 v10, 1.0, v10
	v_div_scale_f32 v11, s[0:1], v10, v10, v8
	v_rcp_f32_e32 v16, v11
	v_add_f32_e32 v7, 1.0, v7
	v_fma_f32 v17, -v11, v16, 1.0
	v_fmac_f32_e32 v16, v17, v16
	v_div_scale_f32 v17, vcc, v8, v10, v8
	v_mul_f32_e32 v18, v17, v16
	v_fma_f32 v19, -v11, v18, v17
	v_fmac_f32_e32 v18, v19, v16
	v_fma_f32 v11, -v11, v18, v17
	v_div_fmas_f32 v11, v11, v16, v18
	v_div_fixup_f32 v8, v11, v10, v8
	v_mul_f32_e32 v8, v9, v8
	v_cvt_pk_bf16_f32 v8, v8, s0
	global_store_short v[4:5], v8, off offset:3200
	v_div_scale_f32 v8, s[0:1], v7, v7, v6
	v_rcp_f32_e32 v9, v8
	s_nop 0
	v_fma_f32 v10, -v8, v9, 1.0
	v_fmac_f32_e32 v9, v10, v9
	v_div_scale_f32 v10, vcc, v6, v7, v6
	v_mul_f32_e32 v11, v10, v9
	v_fma_f32 v12, -v8, v11, v10
	v_fmac_f32_e32 v11, v12, v9
	v_fma_f32 v8, -v8, v11, v10
	v_div_fmas_f32 v8, v8, v9, v11
	v_div_fixup_f32 v6, v8, v7, v6
	v_mul_f32_e32 v0, v0, v6
	v_cvt_pk_bf16_f32 v0, v0, s0
	global_store_short v[4:5], v0, off offset:3264
	v_div_scale_f32 v0, s[0:1], v1, v1, 1.0
	v_rcp_f32_e32 v4, v0
	s_nop 0
	v_fma_f32 v5, -v0, v4, 1.0
	v_fmac_f32_e32 v4, v5, v4
	v_div_scale_f32 v5, vcc, 1.0, v1, 1.0
	v_mul_f32_e32 v6, v5, v4
	v_fma_f32 v7, -v0, v6, v5
	v_fmac_f32_e32 v6, v7, v4
	v_fma_f32 v0, -v0, v6, v5
	v_div_fmas_f32 v0, v0, v4, v6
	v_div_fixup_f32 v6, v0, v1, 1.0
	v_or_b32_e32 v0, 25, v68
	v_mad_u64_u32 v[4:5], s[0:1], v0, s33, v[70:71]
	v_add_u32_e32 v5, s6, v5
	v_lshl_add_u64 v[4:5], v[4:5], 0, s[84:85]
	v_lshl_add_u64 v[8:9], v[4:5], 0, v[176:177]
	v_lshl_add_u64 v[4:5], v[8:9], 0, s[2:3]
	v_add_co_u32_e32 v8, vcc, s63, v8
	v_mov_b32_e32 v1, v69
	s_nop 0
	v_addc_co_u32_e32 v9, vcc, 0, v9, vcc
	s_waitcnt vmcnt(28)
	v_mov_b32_e32 v7, v104
	v_lshlrev_b64 v[0:1], 12, v[0:1]
	v_lshl_add_u64 v[0:1], s[82:83], 0, v[0:1]
	v_mul_f32_e32 v8, v61, v6
	v_lshl_add_u64 v[0:1], v[0:1], 0, s[84:85]
	v_lshl_add_u64 v[0:1], v[0:1], 0, v[176:177]
	s_nop 0
	v_lshlrev_b32_e32 v7, 16, v7
	v_mul_f32_e32 v9, 0xbfb8aa3b, v7
	v_exp_f32_e32 v9, v9
	s_nop 0
	v_add_f32_e32 v9, 1.0, v9
	v_div_scale_f32 v10, s[0:1], v9, v9, v7
	v_rcp_f32_e32 v11, v10
	s_nop 0
	v_fma_f32 v12, -v10, v11, 1.0
	v_fmac_f32_e32 v11, v12, v11
	v_div_scale_f32 v12, vcc, v7, v9, v7
	v_mul_f32_e32 v16, v12, v11
	v_fma_f32 v17, -v10, v16, v12
	v_fmac_f32_e32 v16, v17, v11
	v_fma_f32 v10, -v10, v16, v12
	v_div_fmas_f32 v10, v10, v11, v16
	v_div_fixup_f32 v7, v10, v9, v7
	v_mul_f32_e32 v7, v8, v7
	v_cvt_pk_bf16_f32 v7, v7, s0
	global_store_short v[0:1], v7, off offset:3072
	s_waitcnt vmcnt(28)
	v_mov_b32_e32 v7, v105
	v_mul_f32_e32 v8, v45, v6
	s_nop 0
	v_lshlrev_b32_e32 v7, 16, v7
	v_mul_f32_e32 v9, 0xbfb8aa3b, v7
	v_exp_f32_e32 v9, v9
	s_nop 0
	v_add_f32_e32 v9, 1.0, v9
	v_div_scale_f32 v10, s[0:1], v9, v9, v7
	v_rcp_f32_e32 v11, v10
	s_nop 0
	v_fma_f32 v12, -v10, v11, 1.0
	v_fmac_f32_e32 v11, v12, v11
	v_div_scale_f32 v12, vcc, v7, v9, v7
	v_mul_f32_e32 v16, v12, v11
	v_fma_f32 v17, -v10, v16, v12
	v_fmac_f32_e32 v16, v17, v11
	v_fma_f32 v10, -v10, v16, v12
	v_div_fmas_f32 v10, v10, v11, v16
	v_div_fixup_f32 v7, v10, v9, v7
	v_mul_f32_e32 v7, v8, v7
	v_cvt_pk_bf16_f32 v7, v7, s0
	global_store_short v[0:1], v7, off offset:3136
	s_waitcnt vmcnt(28)
	v_mov_b32_e32 v7, v106
	v_mul_f32_e32 v8, v29, v6
	s_waitcnt vmcnt(28)
	v_mov_b32_e32 v4, v107
	v_mul_f32_e32 v5, v13, v6
	s_nop 0
	v_lshlrev_b32_e32 v7, 16, v7
	v_mul_f32_e32 v9, 0xbfb8aa3b, v7
	v_exp_f32_e32 v9, v9
	s_nop 0
	v_lshlrev_b32_e32 v4, 16, v4
	v_mul_f32_e32 v6, 0xbfb8aa3b, v4
	v_exp_f32_e32 v6, v6
	v_add_f32_e32 v9, 1.0, v9
	v_div_scale_f32 v10, s[0:1], v9, v9, v7
	v_rcp_f32_e32 v11, v10
	v_add_f32_e32 v6, 1.0, v6
	v_fma_f32 v12, -v10, v11, 1.0
	v_fmac_f32_e32 v11, v12, v11
	v_div_scale_f32 v12, vcc, v7, v9, v7
	v_mul_f32_e32 v16, v12, v11
	v_fma_f32 v17, -v10, v16, v12
	v_fmac_f32_e32 v16, v17, v11
	v_fma_f32 v10, -v10, v16, v12
	v_div_fmas_f32 v10, v10, v11, v16
	v_div_fixup_f32 v7, v10, v9, v7
	v_mul_f32_e32 v7, v8, v7
	v_cvt_pk_bf16_f32 v7, v7, s0
	global_store_short v[0:1], v7, off offset:3200
	v_div_scale_f32 v7, s[0:1], v6, v6, v4
	v_rcp_f32_e32 v8, v7
	s_nop 0
	v_fma_f32 v9, -v7, v8, 1.0
	v_fmac_f32_e32 v8, v9, v8
	v_div_scale_f32 v9, vcc, v4, v6, v4
	v_mul_f32_e32 v10, v9, v8
	v_fma_f32 v11, -v7, v10, v9
	v_fmac_f32_e32 v10, v11, v8
	v_fma_f32 v7, -v7, v10, v9
	v_div_fmas_f32 v7, v7, v8, v10
	v_div_fixup_f32 v4, v7, v6, v4
	v_mul_f32_e32 v4, v5, v4
	v_cvt_pk_bf16_f32 v4, v4, s0
	global_store_short v[0:1], v4, off offset:3264
	v_div_scale_f32 v0, s[0:1], v2, v2, 1.0
	v_rcp_f32_e32 v1, v0
	s_nop 0
	v_fma_f32 v4, -v0, v1, 1.0
	v_fmac_f32_e32 v1, v4, v1
	v_div_scale_f32 v4, vcc, 1.0, v2, 1.0
	v_mul_f32_e32 v5, v4, v1
	v_fma_f32 v6, -v0, v5, v4
	v_fmac_f32_e32 v5, v6, v1
	v_fma_f32 v0, -v0, v5, v4
	v_div_fmas_f32 v0, v0, v1, v5
	v_div_fixup_f32 v2, v0, v2, 1.0
	v_or_b32_e32 v0, 26, v68
	v_mad_u64_u32 v[4:5], s[0:1], v0, s33, v[70:71]
	v_add_u32_e32 v5, s6, v5
	v_lshl_add_u64 v[4:5], v[4:5], 0, s[84:85]
	v_lshl_add_u64 v[6:7], v[4:5], 0, v[176:177]
	v_lshl_add_u64 v[4:5], v[6:7], 0, s[2:3]
	v_add_co_u32_e32 v6, vcc, s63, v6
	v_mov_b32_e32 v1, v69
	s_nop 0
	v_addc_co_u32_e32 v7, vcc, 0, v7, vcc
	s_waitcnt vmcnt(28)
; __device__ __forceinline__ int crow(int r, int hi) { return (r & 3) + 8 * (r >> 2) + 4 * hi; }
; __device__ __forceinline__ unsigned cvtpk(float lo, float hi) { f32x2_t v = {lo, hi}; bf16x2_t b = __builtin_convertvector(v, bf16x2_t); return __builtin_bit_cast(unsigned, b); }
; __device__ __forceinline__ float bf2f(unsigned short h) { return __uint_as_float(((unsigned)h) << 16); }
; __device__ __forceinline__ float silu(float x) { return x / (1.0f + __expf(-x)); }
; __device__ __forceinline__ void mem_unit(const MemArgs& A, int unit, char* lds, int wv) {
;     ...
;     if (hi == 0) wsl[r32] = l_reg;
;     asm volatile("s_waitcnt lgkmcnt(0)" ::: "memory");
; #pragma unroll
;     for (int r = 0; r < 16; ++r) { const int rr_ = crow(r, hi); const float rl = 1.0f / wsl[rr_];
;         const bf16* gp = A.proj + (grow0 + rr_) * INC + C_MG + hm * 128 + r32; bf16* yp = A.y + (grow0 + rr_) * DM + Y_M + hm * 128 + r32;
; #pragma unroll
;         for (int d0 = 0; d0 < 4; ++d0) { const float g = bf2f(gp[d0 * 32]); const float val = o[d0][r] * rl * silu(g);
;             yp[d0 * 32] = (bf16)(cvtpk(val, val) & 0xffffu); } }
;     __syncthreads();
	v_mov_b32_e32 v6, v108
	v_lshlrev_b64 v[0:1], 12, v[0:1]
	v_lshl_add_u64 v[0:1], s[82:83], 0, v[0:1]
	v_mul_f32_e32 v7, v62, v2
	v_lshl_add_u64 v[0:1], v[0:1], 0, s[84:85]
	v_lshl_add_u64 v[0:1], v[0:1], 0, v[176:177]
	v_or_b32_e32 v68, 27, v68
	s_nop 0
	v_lshlrev_b32_e32 v6, 16, v6
	v_mul_f32_e32 v8, 0xbfb8aa3b, v6
	v_exp_f32_e32 v8, v8
	s_nop 0
	v_add_f32_e32 v8, 1.0, v8
	v_div_scale_f32 v9, s[0:1], v8, v8, v6
	v_rcp_f32_e32 v10, v9
	s_nop 0
	v_fma_f32 v11, -v9, v10, 1.0
	v_fmac_f32_e32 v10, v11, v10
	v_div_scale_f32 v11, vcc, v6, v8, v6
	v_mul_f32_e32 v12, v11, v10
	v_fma_f32 v13, -v9, v12, v11
	v_fmac_f32_e32 v12, v13, v10
	v_fma_f32 v9, -v9, v12, v11
	v_div_fmas_f32 v9, v9, v10, v12
	v_div_fixup_f32 v6, v9, v8, v6
	v_mul_f32_e32 v6, v7, v6
	v_cvt_pk_bf16_f32 v6, v6, s0
	global_store_short v[0:1], v6, off offset:3072
	s_waitcnt vmcnt(28)
	v_mov_b32_e32 v6, v109
	v_mul_f32_e32 v7, v46, v2
	s_nop 0
	v_lshlrev_b32_e32 v6, 16, v6
	v_mul_f32_e32 v8, 0xbfb8aa3b, v6
	v_exp_f32_e32 v8, v8
	s_nop 0
	v_add_f32_e32 v8, 1.0, v8
	v_div_scale_f32 v9, s[0:1], v8, v8, v6
	v_rcp_f32_e32 v10, v9
	s_nop 0
	v_fma_f32 v11, -v9, v10, 1.0
	v_fmac_f32_e32 v10, v11, v10
	v_div_scale_f32 v11, vcc, v6, v8, v6
	v_mul_f32_e32 v12, v11, v10
	v_fma_f32 v13, -v9, v12, v11
	v_fmac_f32_e32 v12, v13, v10
	v_fma_f32 v9, -v9, v12, v11
	v_div_fmas_f32 v9, v9, v10, v12
	v_div_fixup_f32 v6, v9, v8, v6
	v_mul_f32_e32 v6, v7, v6
	v_cvt_pk_bf16_f32 v6, v6, s0
	global_store_short v[0:1], v6, off offset:3136
	s_waitcnt vmcnt(28)
	v_mov_b32_e32 v6, v110
	v_mul_f32_e32 v7, v30, v2
	s_waitcnt vmcnt(28)
	v_mov_b32_e32 v4, v111
	v_mul_f32_e32 v2, v14, v2
	s_nop 0
	v_lshlrev_b32_e32 v6, 16, v6
	v_mul_f32_e32 v8, 0xbfb8aa3b, v6
	v_exp_f32_e32 v8, v8
	s_nop 0
	v_lshlrev_b32_e32 v4, 16, v4
	v_mul_f32_e32 v5, 0xbfb8aa3b, v4
	v_exp_f32_e32 v5, v5
	v_add_f32_e32 v8, 1.0, v8
	v_div_scale_f32 v9, s[0:1], v8, v8, v6
	v_rcp_f32_e32 v10, v9
	v_add_f32_e32 v5, 1.0, v5
	v_fma_f32 v11, -v9, v10, 1.0
	v_fmac_f32_e32 v10, v11, v10
	v_div_scale_f32 v11, vcc, v6, v8, v6
	v_mul_f32_e32 v12, v11, v10
	v_fma_f32 v13, -v9, v12, v11
	v_fmac_f32_e32 v12, v13, v10
	v_fma_f32 v9, -v9, v12, v11
	v_div_fmas_f32 v9, v9, v10, v12
	v_div_fixup_f32 v6, v9, v8, v6
	v_mul_f32_e32 v6, v7, v6
	v_cvt_pk_bf16_f32 v6, v6, s0
	global_store_short v[0:1], v6, off offset:3200
	v_div_scale_f32 v6, s[0:1], v5, v5, v4
	v_rcp_f32_e32 v7, v6
	s_nop 0
	v_fma_f32 v8, -v6, v7, 1.0
	v_fmac_f32_e32 v7, v8, v7
	v_div_scale_f32 v8, vcc, v4, v5, v4
	v_mul_f32_e32 v9, v8, v7
	v_fma_f32 v10, -v6, v9, v8
	v_fmac_f32_e32 v9, v10, v7
	v_fma_f32 v6, -v6, v9, v8
	v_div_fmas_f32 v6, v6, v7, v9
	v_div_fixup_f32 v4, v6, v5, v4
	v_mul_f32_e32 v2, v2, v4
	v_cvt_pk_bf16_f32 v2, v2, s0
	global_store_short v[0:1], v2, off offset:3264
	v_div_scale_f32 v0, s[0:1], v3, v3, 1.0
	v_rcp_f32_e32 v1, v0
	s_nop 0
	v_fma_f32 v2, -v0, v1, 1.0
	v_fmac_f32_e32 v1, v2, v1
	v_div_scale_f32 v2, vcc, 1.0, v3, 1.0
	v_mul_f32_e32 v4, v2, v1
	v_fma_f32 v5, -v0, v4, v2
	v_fmac_f32_e32 v4, v5, v1
	v_fma_f32 v0, -v0, v4, v2
	v_div_fmas_f32 v0, v0, v1, v4
	v_div_fixup_f32 v4, v0, v3, 1.0
	v_mad_u64_u32 v[0:1], s[0:1], v68, s33, v[70:71]
	v_add_u32_e32 v1, s6, v1
	v_lshl_add_u64 v[0:1], v[0:1], 0, s[84:85]
	v_lshl_add_u64 v[6:7], v[0:1], 0, v[176:177]
	v_lshl_add_u64 v[2:3], v[6:7], 0, s[2:3]
	v_add_co_u32_e32 v6, vcc, s63, v6
	v_lshlrev_b64 v[0:1], 12, v[68:69]
	s_nop 0
	v_addc_co_u32_e32 v7, vcc, 0, v7, vcc
	s_waitcnt vmcnt(28)
	v_mov_b32_e32 v5, v157
	v_lshl_add_u64 v[0:1], s[82:83], 0, v[0:1]
	v_mul_f32_e32 v6, v63, v4
	v_lshl_add_u64 v[0:1], v[0:1], 0, s[84:85]
	v_lshl_add_u64 v[0:1], v[0:1], 0, v[176:177]
	s_mov_b64 s[6:7], 0
	s_nop 0
	v_lshlrev_b32_e32 v5, 16, v5
	v_mul_f32_e32 v7, 0xbfb8aa3b, v5
	v_exp_f32_e32 v7, v7
	s_nop 0
	v_add_f32_e32 v7, 1.0, v7
	v_div_scale_f32 v8, s[0:1], v7, v7, v5
	v_rcp_f32_e32 v9, v8
	s_nop 0
	v_fma_f32 v10, -v8, v9, 1.0
	v_fmac_f32_e32 v9, v10, v9
	v_div_scale_f32 v10, vcc, v5, v7, v5
	v_mul_f32_e32 v11, v10, v9
	v_fma_f32 v12, -v8, v11, v10
	v_fmac_f32_e32 v11, v12, v9
	v_fma_f32 v8, -v8, v11, v10
	v_div_fmas_f32 v8, v8, v9, v11
	v_div_fixup_f32 v5, v8, v7, v5
	v_mul_f32_e32 v5, v6, v5
	v_cvt_pk_bf16_f32 v5, v5, s0
	global_store_short v[0:1], v5, off offset:3072
	s_waitcnt vmcnt(28)
	v_mov_b32_e32 v5, v158
	v_mul_f32_e32 v6, v47, v4
	s_nop 0
	v_lshlrev_b32_e32 v5, 16, v5
	v_mul_f32_e32 v7, 0xbfb8aa3b, v5
	v_exp_f32_e32 v7, v7
	s_nop 0
	v_add_f32_e32 v7, 1.0, v7
	v_div_scale_f32 v8, s[0:1], v7, v7, v5
	v_rcp_f32_e32 v9, v8
	s_nop 0
	v_fma_f32 v10, -v8, v9, 1.0
	v_fmac_f32_e32 v9, v10, v9
	v_div_scale_f32 v10, vcc, v5, v7, v5
	v_mul_f32_e32 v11, v10, v9
	v_fma_f32 v12, -v8, v11, v10
	v_fmac_f32_e32 v11, v12, v9
	v_fma_f32 v8, -v8, v11, v10
	v_div_fmas_f32 v8, v8, v9, v11
	v_div_fixup_f32 v5, v8, v7, v5
	v_mul_f32_e32 v5, v6, v5
	v_cvt_pk_bf16_f32 v5, v5, s0
	global_store_short v[0:1], v5, off offset:3136
	s_waitcnt vmcnt(28)
	v_mov_b32_e32 v5, v159
	v_mul_f32_e32 v6, v31, v4
	s_waitcnt vmcnt(28)
	v_mov_b32_e32 v2, v160
	v_mul_f32_e32 v3, v15, v4
	s_nop 0
	v_lshlrev_b32_e32 v5, 16, v5
	v_mul_f32_e32 v7, 0xbfb8aa3b, v5
	v_exp_f32_e32 v7, v7
	s_nop 0
	v_lshlrev_b32_e32 v2, 16, v2
	v_mul_f32_e32 v4, 0xbfb8aa3b, v2
	v_exp_f32_e32 v4, v4
	v_add_f32_e32 v7, 1.0, v7
	v_div_scale_f32 v8, s[0:1], v7, v7, v5
	v_rcp_f32_e32 v9, v8
	v_add_f32_e32 v4, 1.0, v4
	v_fma_f32 v10, -v8, v9, 1.0
	v_fmac_f32_e32 v9, v10, v9
	v_div_scale_f32 v10, vcc, v5, v7, v5
	v_mul_f32_e32 v11, v10, v9
	v_fma_f32 v12, -v8, v11, v10
	v_fmac_f32_e32 v11, v12, v9
	v_fma_f32 v8, -v8, v11, v10
	v_div_fmas_f32 v8, v8, v9, v11
	v_div_fixup_f32 v5, v8, v7, v5
	v_mul_f32_e32 v5, v6, v5
	v_cvt_pk_bf16_f32 v5, v5, s0
	global_store_short v[0:1], v5, off offset:3200
	v_div_scale_f32 v5, s[0:1], v4, v4, v2
	v_rcp_f32_e32 v6, v5
	s_nop 0
	v_fma_f32 v7, -v5, v6, 1.0
	v_fmac_f32_e32 v6, v7, v6
	v_div_scale_f32 v7, vcc, v2, v4, v2
	v_mul_f32_e32 v8, v7, v6
	v_fma_f32 v9, -v5, v8, v7
	v_fmac_f32_e32 v8, v9, v6
	v_fma_f32 v5, -v5, v8, v7
	v_div_fmas_f32 v5, v5, v6, v8
	v_div_fixup_f32 v2, v5, v4, v2
	v_mul_f32_e32 v2, v3, v2
	v_cvt_pk_bf16_f32 v2, v2, s0
	global_store_short v[0:1], v2, off offset:3264
	s_barrier
